# retU/retO wave-items distributed wave-major over all workgroups (second round no longer packs 8 items on half the CUs)
# speedup vs baseline: 1.0069x; 1.0069x over previous
.LBB0_146:
	s_and_b64 vcc, exec, s[14:15]
	s_cbranch_vccz .LBB0_195
	v_mov_b32_e32 v0, v202
	s_and_b64 s[0:1], s[50:51], exec
	s_movk_i32 s0, 0xc30
	v_ashrrev_i32_e32 v0, 6, v0
	s_cselect_b32 s2, s0, 0xc00
	v_readlane_b32 s0, v252, 4
	s_mov_b64 s[58:59], s[50:51]
	s_nop 0
	v_add_u32_e32 v164, s0, v0
	s_lshr_b32 s12, s0, 3
	s_lshr_b32 s13, s33, 3
	s_cmp_eq_u32 s13, 0x100
	v_mul_lo_u32 v180, v0, s13
	v_add_u32_e32 v180, s12, v180
	s_cselect_b64 vcc, -1, 0
	s_cselect_b32 s12, 0x10000, s33
	s_nop 0
	v_cndmask_b32_e32 v180, v164, v180, vcc
	v_mov_b32_e32 v181, s12
	v_add_u32_e32 v180, s33, v180
	v_cmp_gt_i32_e32 vcc, s2, v164
	s_mov_b64 s[0:1], exec
	v_readlane_b32 s60, v254, 7
	v_readlane_b32 s62, v254, 9
	v_readlane_b32 s63, v254, 10
	v_readlane_b32 s16, v252, 28
	v_readlane_b32 s18, v252, 32
	v_readlane_b32 s62, v255, 12
	s_and_b64 s[14:15], s[0:1], vcc
	v_readlane_b32 s17, v252, 29
	v_readlane_b32 s19, v252, 33
	v_readlane_b32 s13, v254, 2
	s_mov_b32 s22, 0x2aaaaaab
	s_movk_i32 s23, 0x60
	s_mov_b32 s34, 0xa304000
	s_movk_i32 s35, 0x4100
	s_mov_b32 s42, 0x186000
	s_mov_b32 s43, 0x104000
	s_mov_b32 s50, 0x82000
	s_movk_i32 s51, 0x1000
	s_mov_b64 s[52:53], 0x1400
	s_mov_b64 s[54:55], 0xa304500
	v_readlane_b32 s66, v254, 13
	v_readlane_b32 s67, v254, 14
	v_readlane_b32 s68, v254, 15
	v_readlane_b32 s69, v254, 16
	v_readlane_b32 s70, v254, 17
	v_readlane_b32 s71, v254, 18
	v_readlane_b32 s63, v255, 13
	v_readlane_b32 s61, v254, 8
	v_readlane_b32 s64, v254, 11
	v_readlane_b32 s65, v254, 12
	v_readlane_b32 s72, v254, 19
	v_readlane_b32 s73, v254, 20
	v_readlane_b32 s74, v254, 21
	v_readlane_b32 s75, v254, 22
	s_mov_b64 exec, s[14:15]
	s_cbranch_execz .LBB0_150
	s_mul_i32 s12, s62, 0x600
	s_mul_hi_i32 s3, s62, 0x600
	s_add_u32 s38, s70, s12
	s_addc_u32 s39, s71, s3
	v_readlane_b32 s3, v254, 1
	s_mov_b64 s[40:41], 0
	s_nop 0
	v_lshl_add_u32 v165, v0, 5, s3
.LBB0_149:
	v_ashrrev_i32_e32 v0, 2, v164
	v_mul_hi_i32 v2, v0, s22
	v_lshrrev_b32_e32 v4, 31, v2
	v_add_u32_e32 v159, v2, v4
	v_mul_lo_u32 v2, v159, 6
	s_waitcnt vmcnt(0)
	v_sub_u32_e32 v130, v0, v2
	s_mul_i32 s3, s62, 6
	v_add_u32_e32 v4, s3, v130
	v_ashrrev_i32_e32 v5, 31, v4
	v_lshlrev_b64 v[4:5], 2, v[4:5]
	v_mov_b32_e32 v3, v202
	v_lshl_add_u64 v[6:7], s[66:67], 0, v[4:5]
	global_load_dword v178, v[6:7], off
	v_and_b32_e32 v158, 15, v3
	v_bfe_u32 v8, v3, 4, 2
	v_lshlrev_b32_e32 v2, 7, v159
	v_lshl_add_u64 v[4:5], s[68:69], 0, v[4:5]
	v_lshlrev_b32_e32 v98, 6, v130
	global_load_dword v179, v[4:5], off
	v_ashrrev_i32_e32 v99, 31, v98
	v_mov_b64_e32 v[4:5], s[16:17]
	v_lshlrev_b64 v[134:135], 1, v[98:99]
	v_lshlrev_b32_e32 v102, 4, v8
	v_mov_b32_e32 v103, v1
	v_and_or_b32 v168, v165, s23, v158
	v_or_b32_e32 v167, v168, v2
	v_or_b32_e32 v166, 16, v167
	v_lshlrev_b32_e32 v0, 3, v8
	v_mad_i64_i32 v[6:7], s[14:15], v167, s57, v[4:5]
	v_mad_i64_i32 v[8:9], s[14:15], v166, s57, v[4:5]
	v_lshl_add_u64 v[100:101], v[6:7], 0, v[134:135]
	v_lshl_add_u64 v[104:105], v[8:9], 0, v[134:135]
	v_lshl_add_u64 v[6:7], v[100:101], 0, v[102:103]
	v_lshl_add_u64 v[8:9], v[104:105], 0, v[102:103]
	v_lshl_add_u64 v[100:101], v[100:101], 0, v[0:1]
	v_lshl_add_u64 v[106:107], v[100:101], 0, s[52:53]
	v_lshl_add_u64 v[132:133], s[24:25], 0, v[102:103]
	v_or_b32_e32 v171, 16, v168
	v_ashrrev_i32_e32 v131, 31, v130
	v_mov_b32_e32 v173, v1
	v_mov_b32_e32 v175, v1
	v_mov_b32_e32 v164, v180
	v_add_u32_e32 v180, v181, v180
	v_lshlrev_b32_e32 v165, 5, v164
	v_lshlrev_b32_e32 v10, 1, v3
	v_and_b32_e32 v10, 24, v10
	v_and_b32_e32 v3, 3, v3
	v_or3_b32 v3, v3, v10, v2
	v_or_b32_e32 v18, 64, v3
	v_mad_i64_i32 v[18:19], s[14:15], v18, s57, v[4:5]
	v_lshl_add_u64 v[18:19], v[18:19], 0, v[134:135]
	v_lshl_add_u64 v[34:35], v[18:19], 0, v[102:103]
	v_or_b32_e32 v18, 0x44, v3
	v_mad_i64_i32 v[18:19], s[14:15], v18, s57, v[4:5]
	v_lshl_add_u64 v[18:19], v[18:19], 0, v[134:135]
	v_lshl_add_u64 v[36:37], v[18:19], 0, v[102:103]
	v_or_b32_e32 v18, 0x60, v3
	v_mad_i64_i32 v[18:19], s[14:15], v18, s57, v[4:5]
	v_mad_i64_i32 v[10:11], s[14:15], v3, s57, v[4:5]
	v_or_b32_e32 v12, 4, v3
	v_or_b32_e32 v14, 32, v3
	v_or_b32_e32 v16, 36, v3
	v_lshl_add_u64 v[18:19], v[18:19], 0, v[134:135]
	v_or_b32_e32 v3, 0x64, v3
	v_mad_i64_i32 v[12:13], s[14:15], v12, s57, v[4:5]
	v_mad_i64_i32 v[14:15], s[14:15], v14, s57, v[4:5]
	v_mad_i64_i32 v[16:17], s[14:15], v16, s57, v[4:5]
	v_lshl_add_u64 v[94:95], v[18:19], 0, v[102:103]
	v_mad_i64_i32 v[4:5], s[14:15], v3, s57, v[4:5]
	v_or_b32_e32 v18, v98, v158
	v_ashrrev_i32_e32 v3, 31, v2
	v_lshl_add_u64 v[2:3], v[2:3], 1, s[18:19]
	v_mul_lo_u32 v18, v18, s35
	v_lshl_add_u64 v[2:3], v[2:3], 0, v[102:103]
	v_ashrrev_i32_e32 v19, 31, v18
	v_lshl_add_u64 v[110:111], v[18:19], 1, v[2:3]
	v_add_co_u32_e32 v112, vcc, s42, v110
	v_lshl_add_u64 v[12:13], v[12:13], 0, v[134:135]
	s_nop 0
	v_addc_co_u32_e32 v113, vcc, 0, v111, vcc
	v_add_co_u32_e32 v152, vcc, s43, v110
	v_lshl_add_u64 v[10:11], v[10:11], 0, v[134:135]
	v_lshl_add_u64 v[12:13], v[12:13], 0, v[102:103]
	v_lshl_add_u64 v[14:15], v[14:15], 0, v[134:135]
	v_lshl_add_u64 v[16:17], v[16:17], 0, v[134:135]
	v_addc_co_u32_e32 v153, vcc, 0, v111, vcc
	v_lshl_add_u64 v[10:11], v[10:11], 0, v[102:103]
	v_lshl_add_u64 v[14:15], v[14:15], 0, v[102:103]
	v_lshl_add_u64 v[16:17], v[16:17], 0, v[102:103]
	v_lshl_add_u64 v[4:5], v[4:5], 0, v[134:135]
	global_load_dwordx4 v[66:69], v[12:13], off offset:3648
	global_load_dwordx4 v[70:73], v[12:13], off offset:3584
	global_load_dwordx4 v[74:77], v[10:11], off offset:3648
	global_load_dwordx4 v[78:81], v[10:11], off offset:3584
	global_load_dwordx4 v[18:21], v[8:9], off offset:2880
	global_load_dwordx4 v[26:29], v[8:9], off offset:2816
	global_load_dwordx4 v[22:25], v[6:7], off offset:2880
	global_load_dwordx4 v[30:33], v[6:7], off offset:2816
	global_load_dwordx4 v[114:117], v[36:37], off offset:3648
	global_load_dwordx4 v[118:121], v[36:37], off offset:3584
	global_load_dwordx4 v[122:125], v[34:35], off offset:3648
	global_load_dwordx4 v[126:129], v[34:35], off offset:3584
	s_nop 0
	global_load_dwordx4 v[34:37], v[16:17], off offset:3648
	global_load_dwordx4 v[38:41], v[16:17], off offset:3584
	global_load_dwordx4 v[42:45], v[14:15], off offset:3648
	global_load_dwordx4 v[46:49], v[14:15], off offset:3584
	v_add_co_u32_e32 v154, vcc, s50, v110
	v_lshl_add_u64 v[4:5], v[4:5], 0, v[102:103]
	s_nop 0
	v_addc_co_u32_e32 v155, vcc, 0, v111, vcc
	global_load_dwordx4 v[50:53], v[112:113], off
	global_load_dwordx4 v[54:57], v[152:153], off
	global_load_dwordx4 v[58:61], v[154:155], off
	global_load_dwordx4 v[62:65], v[110:111], off
	global_load_dwordx4 v[82:85], v[4:5], off offset:3648
	global_load_dwordx4 v[86:89], v[4:5], off offset:3584
	global_load_dwordx4 v[90:93], v[94:95], off offset:3648
	s_nop 0
	global_load_dwordx4 v[94:97], v[94:95], off offset:3584
	s_nop 0
	global_load_dwordx4 v[2:5], v[112:113], off offset:64
	global_load_dwordx4 v[6:9], v[152:153], off offset:64
	global_load_dwordx4 v[10:13], v[154:155], off offset:64
	global_load_dwordx4 v[14:17], v[110:111], off offset:64
	v_add_co_u32_e32 v100, vcc, s51, v100
	v_lshl_add_u64 v[98:99], v[98:99], 2, s[38:39]
	s_nop 0
	v_addc_co_u32_e32 v101, vcc, 0, v101, vcc
	v_lshl_add_u64 v[156:157], v[98:99], 0, v[102:103]
	v_or_b32_e32 v108, 7, v0
	s_waitcnt vmcnt(0)
	v_mul_f32_e32 v169, 0x3fb8aa3b, v178
	v_mul_f32_e32 v170, 0x3fb8aa3b, v179
	global_load_dwordx2 v[150:151], v[100:101], off offset:1024
	global_load_dwordx2 v[148:149], v[106:107], off offset:32
	global_load_dwordx2 v[146:147], v[106:107], off offset:64
	global_load_dwordx2 v[144:145], v[106:107], off offset:96
	v_lshl_add_u64 v[100:101], v[104:105], 0, v[0:1]
	v_lshl_add_u64 v[104:105], v[100:101], 0, s[52:53]
	v_add_co_u32_e32 v100, vcc, s51, v100
	v_or_b32_e32 v106, 5, v0
	s_nop 0
	v_addc_co_u32_e32 v101, vcc, 0, v101, vcc
	global_load_dwordx2 v[142:143], v[100:101], off offset:1024
	global_load_dwordx2 v[140:141], v[104:105], off offset:32
	global_load_dwordx2 v[138:139], v[104:105], off offset:64
	global_load_dwordx2 v[136:137], v[104:105], off offset:96
	v_mfma_f32_16x16x32_bf16 v[98:101], v[78:81], v[30:33], 0
	v_or_b32_e32 v107, 6, v0
	v_mfma_f32_16x16x32_bf16 v[78:81], v[78:81], v[26:29], 0
	v_mfma_f32_16x16x32_bf16 v[98:101], v[74:77], v[22:25], v[98:101]
	v_mfma_f32_16x16x32_bf16 v[74:77], v[74:77], v[18:21], v[78:81]
	v_mfma_f32_16x16x32_bf16 v[78:81], v[70:73], v[30:33], 0
	v_mfma_f32_16x16x32_bf16 v[70:73], v[70:73], v[26:29], 0
	v_mfma_f32_16x16x32_bf16 v[78:81], v[66:69], v[22:25], v[78:81]
	v_mfma_f32_16x16x32_bf16 v[66:69], v[66:69], v[18:21], v[70:73]
	s_nop 5
	v_sub_u32_e32 v71, v168, v0
	v_cvt_f32_u32_e32 v72, v71
	v_cmp_lt_i32_e32 vcc, -1, v71
	v_or_b32_e32 v70, 4, v0
	v_mul_f32_e32 v72, v169, v72
	v_exp_f32_e32 v72, v72
	s_nop 0
	v_cndmask_b32_e32 v72, 0, v72, vcc
	v_cmp_gt_i32_e32 vcc, 1, v71
	v_sub_u32_e32 v71, 0, v71
	v_cvt_f32_u32_e32 v71, v71
	v_mul_f32_e32 v71, v170, v71
	v_exp_f32_e32 v71, v71
	s_nop 0
	v_cndmask_b32_e32 v71, 0, v71, vcc
	v_add_f32_e32 v71, v72, v71
	v_or_b32_e32 v72, 1, v0
	v_sub_u32_e32 v73, v168, v72
	v_mul_f32_e32 v71, v71, v98
	v_cvt_f32_u32_e32 v98, v73
	v_cmp_lt_i32_e32 vcc, -1, v73
	v_sub_u32_e32 v72, v171, v72
	v_mul_f32_e32 v98, v169, v98
	v_exp_f32_e32 v98, v98
	s_nop 0
	v_cndmask_b32_e32 v98, 0, v98, vcc
	v_cmp_gt_i32_e32 vcc, 1, v73
	v_sub_u32_e32 v73, 0, v73
	v_cvt_f32_u32_e32 v73, v73
	v_mul_f32_e32 v73, v170, v73
	v_exp_f32_e32 v73, v73
	s_nop 0
	v_cndmask_b32_e32 v73, 0, v73, vcc
	v_add_f32_e32 v73, v98, v73
	v_or_b32_e32 v98, 2, v0
	v_mul_f32_e32 v73, v73, v99
	v_sub_u32_e32 v99, v168, v98
	v_cvt_f32_u32_e32 v102, v99
	v_cmp_lt_i32_e32 vcc, -1, v99
	v_mul_f32_e32 v102, v169, v102
	v_exp_f32_e32 v102, v102
	s_nop 0
	v_cndmask_b32_e32 v102, 0, v102, vcc
	v_cmp_gt_i32_e32 vcc, 1, v99
	v_sub_u32_e32 v99, 0, v99
	v_cvt_f32_u32_e32 v99, v99
	v_mul_f32_e32 v99, v170, v99
	v_exp_f32_e32 v99, v99
	s_nop 0
	v_cndmask_b32_e32 v99, 0, v99, vcc
	v_add_f32_e32 v99, v102, v99
	v_mul_f32_e32 v99, v99, v100
	v_or_b32_e32 v100, 3, v0
	v_sub_u32_e32 v102, v168, v100
	v_cvt_f32_u32_e32 v103, v102
	v_cmp_lt_i32_e32 vcc, -1, v102
	v_mul_f32_e32 v103, v169, v103
	v_exp_f32_e32 v103, v103
	s_nop 0
	v_cndmask_b32_e32 v103, 0, v103, vcc
	v_cmp_gt_i32_e32 vcc, 1, v102
	v_sub_u32_e32 v102, 0, v102
	v_cvt_f32_u32_e32 v102, v102
	v_mul_f32_e32 v102, v170, v102
	v_exp_f32_e32 v102, v102
	s_nop 0
	v_cndmask_b32_e32 v102, 0, v102, vcc
	v_add_f32_e32 v102, v103, v102
	v_mul_f32_e32 v101, v102, v101
	v_sub_u32_e32 v102, v168, v70
	v_cvt_f32_u32_e32 v103, v102
	v_cmp_lt_i32_e32 vcc, -1, v102
	v_sub_u32_e32 v70, v171, v70
	v_mul_f32_e32 v103, v169, v103
	v_exp_f32_e32 v103, v103
	s_nop 0
	v_cndmask_b32_e32 v103, 0, v103, vcc
	v_cmp_gt_i32_e32 vcc, 1, v102
	v_sub_u32_e32 v102, 0, v102
	v_cvt_f32_u32_e32 v102, v102
	v_mul_f32_e32 v102, v170, v102
	v_exp_f32_e32 v102, v102
	s_nop 0
	v_cndmask_b32_e32 v102, 0, v102, vcc
	v_add_f32_e32 v102, v103, v102
	v_mul_f32_e32 v78, v102, v78
	v_sub_u32_e32 v102, v168, v106
	v_cvt_f32_u32_e32 v103, v102
	v_cmp_lt_i32_e32 vcc, -1, v102
	v_mul_f32_e32 v103, v169, v103
	v_exp_f32_e32 v103, v103
	s_nop 0
	v_cndmask_b32_e32 v103, 0, v103, vcc
	v_cmp_gt_i32_e32 vcc, 1, v102
	v_sub_u32_e32 v102, 0, v102
	v_cvt_f32_u32_e32 v102, v102
	v_mul_f32_e32 v102, v170, v102
	v_exp_f32_e32 v102, v102
	s_nop 0
	v_cndmask_b32_e32 v102, 0, v102, vcc
	v_add_f32_e32 v102, v103, v102
	v_mul_f32_e32 v79, v102, v79
	v_sub_u32_e32 v102, v168, v107
	v_cvt_f32_u32_e32 v103, v102
	v_cmp_lt_i32_e32 vcc, -1, v102
	v_cvt_pk_bf16_f32 v104, v78, v79
	v_mul_f32_e32 v103, v169, v103
	v_exp_f32_e32 v103, v103
	s_nop 0
	v_cndmask_b32_e32 v103, 0, v103, vcc
	v_cmp_gt_i32_e32 vcc, 1, v102
	v_sub_u32_e32 v102, 0, v102
	v_cvt_f32_u32_e32 v102, v102
	v_mul_f32_e32 v102, v170, v102
	v_exp_f32_e32 v102, v102
	s_nop 0
	v_cndmask_b32_e32 v102, 0, v102, vcc
	v_add_f32_e32 v102, v103, v102
	v_mul_f32_e32 v80, v102, v80
	v_sub_u32_e32 v102, v168, v108
	v_cvt_f32_u32_e32 v103, v102
	v_cmp_lt_i32_e32 vcc, -1, v102
	v_mul_f32_e32 v103, v169, v103
	v_exp_f32_e32 v103, v103
	s_nop 0
	v_cndmask_b32_e32 v103, 0, v103, vcc
	v_cmp_gt_i32_e32 vcc, 1, v102
	v_sub_u32_e32 v102, 0, v102
	v_cvt_f32_u32_e32 v102, v102
	v_mul_f32_e32 v102, v170, v102
	v_exp_f32_e32 v102, v102
	s_nop 0
	v_cndmask_b32_e32 v102, 0, v102, vcc
	v_add_f32_e32 v102, v103, v102
	v_mul_f32_e32 v81, v102, v81
	v_cvt_pk_bf16_f32 v102, v71, v73
	v_sub_u32_e32 v71, v171, v0
	v_cvt_f32_u32_e32 v73, v71
	v_cmp_lt_i32_e32 vcc, -1, v71
	v_cvt_pk_bf16_f32 v103, v99, v101
	v_cvt_pk_bf16_f32 v105, v80, v81
	v_mul_f32_e32 v73, v169, v73
	v_exp_f32_e32 v73, v73
	v_mfma_f32_16x16x32_bf16 v[78:81], v[54:57], v[102:105], 0
	v_cndmask_b32_e32 v73, 0, v73, vcc
	v_cmp_gt_i32_e32 vcc, 1, v71
	v_sub_u32_e32 v71, 0, v71
	v_cvt_f32_u32_e32 v71, v71
	v_mul_f32_e32 v71, v170, v71
	v_exp_f32_e32 v71, v71
	s_nop 0
	v_cndmask_b32_e32 v71, 0, v71, vcc
	v_add_f32_e32 v71, v73, v71
	v_cvt_f32_u32_e32 v73, v72
	v_cmp_lt_i32_e32 vcc, -1, v72
	v_mul_f32_e32 v71, v71, v74
	v_mul_f32_e32 v73, v169, v73
	v_exp_f32_e32 v73, v73
	s_nop 0
	v_cndmask_b32_e32 v73, 0, v73, vcc
	v_cmp_gt_i32_e32 vcc, 1, v72
	v_sub_u32_e32 v72, 0, v72
	v_cvt_f32_u32_e32 v72, v72
	v_mul_f32_e32 v72, v170, v72
	v_exp_f32_e32 v72, v72
	s_nop 0
	v_cndmask_b32_e32 v72, 0, v72, vcc
	v_add_f32_e32 v72, v73, v72
	v_sub_u32_e32 v73, v171, v98
	v_cvt_f32_u32_e32 v74, v73
	v_cmp_lt_i32_e32 vcc, -1, v73
	v_mul_f32_e32 v72, v72, v75
	v_mul_f32_e32 v74, v169, v74
	v_exp_f32_e32 v74, v74
	s_nop 0
	v_cndmask_b32_e32 v74, 0, v74, vcc
	v_cmp_gt_i32_e32 vcc, 1, v73
	v_sub_u32_e32 v73, 0, v73
	v_cvt_f32_u32_e32 v73, v73
	v_mul_f32_e32 v73, v170, v73
	v_exp_f32_e32 v73, v73
	s_nop 0
	v_cndmask_b32_e32 v73, 0, v73, vcc
	v_add_f32_e32 v73, v74, v73
	v_sub_u32_e32 v74, v171, v100
	v_cvt_f32_u32_e32 v75, v74
	v_cmp_lt_i32_e32 vcc, -1, v74
	v_mul_f32_e32 v73, v73, v76
	v_mul_f32_e32 v75, v169, v75
	v_exp_f32_e32 v75, v75
	s_nop 0
	v_cndmask_b32_e32 v75, 0, v75, vcc
	v_cmp_gt_i32_e32 vcc, 1, v74
	v_sub_u32_e32 v74, 0, v74
	v_cvt_f32_u32_e32 v74, v74
	v_mul_f32_e32 v74, v170, v74
	v_exp_f32_e32 v74, v74
	s_nop 0
	v_cndmask_b32_e32 v74, 0, v74, vcc
	v_add_f32_e32 v74, v75, v74
	v_cvt_f32_u32_e32 v75, v70
	v_cmp_lt_i32_e32 vcc, -1, v70
	v_mul_f32_e32 v74, v74, v77
	v_mul_f32_e32 v75, v169, v75
	v_exp_f32_e32 v75, v75
	s_nop 0
	v_cndmask_b32_e32 v75, 0, v75, vcc
	v_cmp_gt_i32_e32 vcc, 1, v70
	v_sub_u32_e32 v70, 0, v70
	v_cvt_f32_u32_e32 v70, v70
	v_mul_f32_e32 v70, v170, v70
	v_exp_f32_e32 v70, v70
	s_nop 0
	v_cndmask_b32_e32 v70, 0, v70, vcc
	v_add_f32_e32 v70, v75, v70
	v_mul_f32_e32 v66, v70, v66
	v_sub_u32_e32 v70, v171, v106
	v_cvt_f32_u32_e32 v75, v70
	v_cmp_lt_i32_e32 vcc, -1, v70
	v_cvt_pk_bf16_f32 v106, v71, v72
	v_mul_f32_e32 v75, v169, v75
	v_exp_f32_e32 v75, v75
	s_nop 0
	v_cndmask_b32_e32 v75, 0, v75, vcc
	v_cmp_gt_i32_e32 vcc, 1, v70
	v_sub_u32_e32 v70, 0, v70
	v_cvt_f32_u32_e32 v70, v70
	v_mul_f32_e32 v70, v170, v70
	v_exp_f32_e32 v70, v70
	s_nop 0
	v_cndmask_b32_e32 v70, 0, v70, vcc
	v_add_f32_e32 v70, v75, v70
	v_mul_f32_e32 v67, v70, v67
	v_sub_u32_e32 v70, v171, v107
	v_cvt_f32_u32_e32 v75, v70
	v_cmp_lt_i32_e32 vcc, -1, v70
	v_cvt_pk_bf16_f32 v107, v73, v74
	v_mul_f32_e32 v75, v169, v75
	v_exp_f32_e32 v75, v75
	s_nop 0
	v_cndmask_b32_e32 v75, 0, v75, vcc
	v_cmp_gt_i32_e32 vcc, 1, v70
	v_sub_u32_e32 v70, 0, v70
	v_cvt_f32_u32_e32 v70, v70
	v_mul_f32_e32 v70, v170, v70
	v_exp_f32_e32 v70, v70
	s_nop 0
	v_cndmask_b32_e32 v70, 0, v70, vcc
	v_add_f32_e32 v70, v75, v70
	v_mul_f32_e32 v68, v70, v68
	v_sub_u32_e32 v70, v171, v108
	v_cvt_f32_u32_e32 v75, v70
	v_cmp_lt_i32_e32 vcc, -1, v70
	v_cvt_pk_bf16_f32 v108, v66, v67
	v_mul_f32_e32 v75, v169, v75
	v_exp_f32_e32 v75, v75
	s_nop 0
	v_cndmask_b32_e32 v75, 0, v75, vcc
	v_cmp_gt_i32_e32 vcc, 1, v70
	v_sub_u32_e32 v70, 0, v70
	v_cvt_f32_u32_e32 v70, v70
	v_mul_f32_e32 v70, v170, v70
	v_exp_f32_e32 v70, v70
	s_nop 0
	v_cndmask_b32_e32 v70, 0, v70, vcc
	v_add_f32_e32 v70, v75, v70
	v_mul_f32_e32 v69, v70, v69
	v_cvt_pk_bf16_f32 v109, v68, v69
	v_mfma_f32_16x16x32_bf16 v[66:69], v[62:65], v[102:105], 0
	v_mfma_f32_16x16x32_bf16 v[62:65], v[62:65], v[106:109], 0
	v_mfma_f32_16x16x32_bf16 v[70:73], v[58:61], v[102:105], 0
	v_mfma_f32_16x16x32_bf16 v[74:77], v[58:61], v[106:109], 0
	v_mfma_f32_16x16x32_bf16 v[98:101], v[54:57], v[106:109], 0
	v_or_b32_e32 v55, 32, v0
	v_or_b32_e32 v54, 36, v0
	v_mfma_f32_16x16x32_bf16 v[102:105], v[50:53], v[102:105], 0
	v_mfma_f32_16x16x32_bf16 v[106:109], v[50:53], v[106:109], 0
	v_mfma_f32_16x16x32_bf16 v[50:53], v[46:49], v[30:33], 0
	v_mfma_f32_16x16x32_bf16 v[46:49], v[46:49], v[26:29], 0
	v_mfma_f32_16x16x32_bf16 v[50:53], v[42:45], v[22:25], v[50:53]
	v_mfma_f32_16x16x32_bf16 v[42:45], v[42:45], v[18:21], v[46:49]
	v_mfma_f32_16x16x32_bf16 v[46:49], v[38:41], v[30:33], 0
	v_mfma_f32_16x16x32_bf16 v[38:41], v[38:41], v[26:29], 0
	v_mfma_f32_16x16x32_bf16 v[46:49], v[34:37], v[22:25], v[46:49]
	v_mfma_f32_16x16x32_bf16 v[34:37], v[34:37], v[18:21], v[38:41]
	s_nop 5
	v_sub_u32_e32 v38, v168, v55
	v_cvt_f32_u32_e32 v39, v38
	v_cmp_lt_i32_e32 vcc, -1, v38
	v_mul_f32_e32 v39, v169, v39
	v_exp_f32_e32 v39, v39
	s_nop 0
	v_cndmask_b32_e32 v39, 0, v39, vcc
	v_cmp_gt_i32_e32 vcc, 1, v38
	v_sub_u32_e32 v38, 0, v38
	v_cvt_f32_u32_e32 v38, v38
	v_mul_f32_e32 v38, v170, v38
	v_exp_f32_e32 v38, v38
	s_nop 0
	v_cndmask_b32_e32 v38, 0, v38, vcc
	v_add_f32_e32 v38, v39, v38
	v_mul_f32_e32 v38, v38, v50
	v_or_b32_e32 v50, 33, v0
	v_sub_u32_e32 v39, v168, v50
	v_cvt_f32_u32_e32 v40, v39
	v_cmp_lt_i32_e32 vcc, -1, v39
	v_mul_f32_e32 v40, v169, v40
	v_exp_f32_e32 v40, v40
	s_nop 0
	v_cndmask_b32_e32 v40, 0, v40, vcc
	v_cmp_gt_i32_e32 vcc, 1, v39
	v_sub_u32_e32 v39, 0, v39
	v_cvt_f32_u32_e32 v39, v39
	v_mul_f32_e32 v39, v170, v39
	v_exp_f32_e32 v39, v39
	s_nop 0
	v_cndmask_b32_e32 v39, 0, v39, vcc
	v_add_f32_e32 v39, v40, v39
	v_mul_f32_e32 v39, v39, v51
	v_or_b32_e32 v51, 34, v0
	v_sub_u32_e32 v40, v168, v51
	v_cvt_f32_u32_e32 v41, v40
	v_cmp_lt_i32_e32 vcc, -1, v40
	v_cvt_pk_bf16_f32 v38, v38, v39
	v_mul_f32_e32 v41, v169, v41
	v_exp_f32_e32 v41, v41
	s_nop 0
	v_cndmask_b32_e32 v41, 0, v41, vcc
	v_cmp_gt_i32_e32 vcc, 1, v40
	v_sub_u32_e32 v40, 0, v40
	v_cvt_f32_u32_e32 v40, v40
	v_mul_f32_e32 v40, v170, v40
	v_exp_f32_e32 v40, v40
	s_nop 0
	v_cndmask_b32_e32 v40, 0, v40, vcc
	v_add_f32_e32 v40, v41, v40
	v_mul_f32_e32 v40, v40, v52
	v_or_b32_e32 v52, 35, v0
	v_sub_u32_e32 v41, v168, v52
	v_cvt_f32_u32_e32 v56, v41
	v_cmp_lt_i32_e32 vcc, -1, v41
	v_mul_f32_e32 v56, v169, v56
	v_exp_f32_e32 v56, v56
	s_nop 0
	v_cndmask_b32_e32 v56, 0, v56, vcc
	v_cmp_gt_i32_e32 vcc, 1, v41
	v_sub_u32_e32 v41, 0, v41
	v_cvt_f32_u32_e32 v41, v41
	v_mul_f32_e32 v41, v170, v41
	v_exp_f32_e32 v41, v41
	s_nop 0
	v_cndmask_b32_e32 v41, 0, v41, vcc
	v_add_f32_e32 v41, v56, v41
	v_mul_f32_e32 v41, v41, v53
	v_sub_u32_e32 v53, v168, v54
	v_cvt_f32_u32_e32 v56, v53
	v_cmp_lt_i32_e32 vcc, -1, v53
	v_cvt_pk_bf16_f32 v39, v40, v41
	v_mul_f32_e32 v56, v169, v56
	v_exp_f32_e32 v56, v56
	s_nop 0
	v_cndmask_b32_e32 v56, 0, v56, vcc
	v_cmp_gt_i32_e32 vcc, 1, v53
	v_sub_u32_e32 v53, 0, v53
	v_cvt_f32_u32_e32 v53, v53
	v_mul_f32_e32 v53, v170, v53
	v_exp_f32_e32 v53, v53
	s_nop 0
	v_cndmask_b32_e32 v53, 0, v53, vcc
	v_add_f32_e32 v53, v56, v53
	v_mul_f32_e32 v46, v53, v46
	v_or_b32_e32 v53, 37, v0
	v_sub_u32_e32 v56, v168, v53
	v_cvt_f32_u32_e32 v57, v56
	v_cmp_lt_i32_e32 vcc, -1, v56
	v_mul_f32_e32 v57, v169, v57
	v_exp_f32_e32 v57, v57
	s_nop 0
	v_cndmask_b32_e32 v57, 0, v57, vcc
	v_cmp_gt_i32_e32 vcc, 1, v56
	v_sub_u32_e32 v56, 0, v56
	v_cvt_f32_u32_e32 v56, v56
	v_mul_f32_e32 v56, v170, v56
	v_exp_f32_e32 v56, v56
	s_nop 0
	v_cndmask_b32_e32 v56, 0, v56, vcc
	v_add_f32_e32 v56, v57, v56
	v_mul_f32_e32 v47, v56, v47
	v_or_b32_e32 v56, 38, v0
	v_sub_u32_e32 v57, v168, v56
	v_cvt_f32_u32_e32 v58, v57
	v_cmp_lt_i32_e32 vcc, -1, v57
	v_cvt_pk_bf16_f32 v40, v46, v47
	v_sub_u32_e32 v46, v171, v55
	v_mul_f32_e32 v58, v169, v58
	v_exp_f32_e32 v58, v58
	v_cvt_f32_u32_e32 v47, v46
	v_cndmask_b32_e32 v58, 0, v58, vcc
	v_cmp_gt_i32_e32 vcc, 1, v57
	v_sub_u32_e32 v57, 0, v57
	v_cvt_f32_u32_e32 v57, v57
	v_mul_f32_e32 v47, v169, v47
	v_exp_f32_e32 v47, v47
	v_mul_f32_e32 v57, v170, v57
	v_exp_f32_e32 v57, v57
	s_nop 0
	v_cndmask_b32_e32 v57, 0, v57, vcc
	v_add_f32_e32 v57, v58, v57
	v_mul_f32_e32 v48, v57, v48
	v_or_b32_e32 v57, 39, v0
	v_sub_u32_e32 v58, v168, v57
	v_cvt_f32_u32_e32 v59, v58
	v_cmp_lt_i32_e32 vcc, -1, v58
	v_mul_f32_e32 v59, v169, v59
	v_exp_f32_e32 v59, v59
	s_nop 0
	v_cndmask_b32_e32 v59, 0, v59, vcc
	v_cmp_gt_i32_e32 vcc, 1, v58
	v_sub_u32_e32 v58, 0, v58
	v_cvt_f32_u32_e32 v58, v58
	v_mul_f32_e32 v58, v170, v58
	v_exp_f32_e32 v58, v58
	s_nop 0
	v_cndmask_b32_e32 v58, 0, v58, vcc
	v_cmp_lt_i32_e32 vcc, -1, v46
	v_add_f32_e32 v58, v59, v58
	v_mul_f32_e32 v49, v58, v49
	v_cndmask_b32_e32 v47, 0, v47, vcc
	v_cmp_gt_i32_e32 vcc, 1, v46
	v_sub_u32_e32 v46, 0, v46
	v_cvt_f32_u32_e32 v46, v46
	v_cvt_pk_bf16_f32 v41, v48, v49
	v_mul_f32_e32 v46, v170, v46
	v_exp_f32_e32 v46, v46
	v_mfma_f32_16x16x32_bf16 v[58:61], v[10:13], v[38:41], v[70:73]
	v_cndmask_b32_e32 v46, 0, v46, vcc
	v_add_f32_e32 v46, v47, v46
	v_mul_f32_e32 v42, v46, v42
	v_sub_u32_e32 v46, v171, v50
	v_cvt_f32_u32_e32 v47, v46
	v_cmp_lt_i32_e32 vcc, -1, v46
	v_mul_f32_e32 v47, v169, v47
	v_exp_f32_e32 v47, v47
	s_nop 0
	v_cndmask_b32_e32 v47, 0, v47, vcc
	v_cmp_gt_i32_e32 vcc, 1, v46
	v_sub_u32_e32 v46, 0, v46
	v_cvt_f32_u32_e32 v46, v46
	v_mul_f32_e32 v46, v170, v46
	v_exp_f32_e32 v46, v46
	s_nop 0
	v_cndmask_b32_e32 v46, 0, v46, vcc
	v_add_f32_e32 v46, v47, v46
	v_mul_f32_e32 v43, v46, v43
	v_sub_u32_e32 v46, v171, v51
	v_cvt_f32_u32_e32 v47, v46
	v_cmp_lt_i32_e32 vcc, -1, v46
	v_mul_f32_e32 v47, v169, v47
	v_exp_f32_e32 v47, v47
	s_nop 0
	v_cndmask_b32_e32 v47, 0, v47, vcc
	v_cmp_gt_i32_e32 vcc, 1, v46
	v_sub_u32_e32 v46, 0, v46
	v_cvt_f32_u32_e32 v46, v46
	v_mul_f32_e32 v46, v170, v46
	v_exp_f32_e32 v46, v46
	s_nop 0
	v_cndmask_b32_e32 v46, 0, v46, vcc
	v_add_f32_e32 v46, v47, v46
	v_mul_f32_e32 v44, v46, v44
	v_sub_u32_e32 v46, v171, v52
	v_cvt_f32_u32_e32 v47, v46
	v_cmp_lt_i32_e32 vcc, -1, v46
	v_mul_f32_e32 v47, v169, v47
	v_exp_f32_e32 v47, v47
	s_nop 0
	v_cndmask_b32_e32 v47, 0, v47, vcc
	v_cmp_gt_i32_e32 vcc, 1, v46
	v_sub_u32_e32 v46, 0, v46
	v_cvt_f32_u32_e32 v46, v46
	v_mul_f32_e32 v46, v170, v46
	v_exp_f32_e32 v46, v46
	s_nop 0
	v_cndmask_b32_e32 v46, 0, v46, vcc
	v_add_f32_e32 v46, v47, v46
	v_mul_f32_e32 v45, v46, v45
	v_sub_u32_e32 v46, v171, v54
	v_cvt_f32_u32_e32 v47, v46
	v_cmp_lt_i32_e32 vcc, -1, v46
	v_mul_f32_e32 v47, v169, v47
	v_exp_f32_e32 v47, v47
	s_nop 0
	v_cndmask_b32_e32 v47, 0, v47, vcc
	v_cmp_gt_i32_e32 vcc, 1, v46
	v_sub_u32_e32 v46, 0, v46
	v_cvt_f32_u32_e32 v46, v46
	v_mul_f32_e32 v46, v170, v46
	v_exp_f32_e32 v46, v46
	s_nop 0
	v_cndmask_b32_e32 v46, 0, v46, vcc
	v_add_f32_e32 v46, v47, v46
	v_mul_f32_e32 v46, v46, v34
	v_sub_u32_e32 v34, v171, v53
	v_cvt_f32_u32_e32 v47, v34
	v_cmp_lt_i32_e32 vcc, -1, v34
	v_mfma_f32_16x16x32_bf16 v[50:53], v[14:17], v[38:41], v[66:69]
	v_mul_f32_e32 v47, v169, v47
	v_exp_f32_e32 v47, v47
	v_mfma_f32_16x16x32_bf16 v[66:69], v[6:9], v[38:41], v[78:81]
	v_cndmask_b32_e32 v47, 0, v47, vcc
	v_cmp_gt_i32_e32 vcc, 1, v34
	v_sub_u32_e32 v34, 0, v34
	v_cvt_f32_u32_e32 v34, v34
	v_mul_f32_e32 v34, v170, v34
	v_exp_f32_e32 v34, v34
	s_nop 0
	v_cndmask_b32_e32 v34, 0, v34, vcc
	v_add_f32_e32 v34, v47, v34
	v_mul_f32_e32 v47, v34, v35
	v_sub_u32_e32 v34, v171, v56
	v_cvt_f32_u32_e32 v35, v34
	v_cmp_lt_i32_e32 vcc, -1, v34
	v_mul_f32_e32 v35, v169, v35
	v_exp_f32_e32 v35, v35
	s_nop 0
	v_cndmask_b32_e32 v35, 0, v35, vcc
	v_cmp_gt_i32_e32 vcc, 1, v34
	v_sub_u32_e32 v34, 0, v34
	v_cvt_f32_u32_e32 v34, v34
	v_mul_f32_e32 v34, v170, v34
	v_exp_f32_e32 v34, v34
	s_nop 0
	v_cndmask_b32_e32 v34, 0, v34, vcc
	v_add_f32_e32 v34, v35, v34
	v_mul_f32_e32 v48, v34, v36
	v_sub_u32_e32 v34, v171, v57
	v_cvt_f32_u32_e32 v35, v34
	v_cmp_lt_i32_e32 vcc, -1, v34
	v_cvt_pk_bf16_f32 v36, v46, v47
	v_mul_f32_e32 v35, v169, v35
	v_exp_f32_e32 v35, v35
	s_nop 0
	v_cndmask_b32_e32 v35, 0, v35, vcc
	v_cmp_gt_i32_e32 vcc, 1, v34
	v_sub_u32_e32 v34, 0, v34
	v_cvt_f32_u32_e32 v34, v34
	v_mul_f32_e32 v34, v170, v34
	v_exp_f32_e32 v34, v34
	s_nop 0
	v_cndmask_b32_e32 v34, 0, v34, vcc
	v_add_f32_e32 v34, v35, v34
	v_mul_f32_e32 v37, v34, v37
	v_cvt_pk_bf16_f32 v34, v42, v43
	v_cvt_pk_bf16_f32 v35, v44, v45
	v_cvt_pk_bf16_f32 v37, v48, v37
	s_nop 1
	v_mfma_f32_16x16x32_bf16 v[54:57], v[14:17], v[34:37], v[62:65]
	v_mfma_f32_16x16x32_bf16 v[62:65], v[10:13], v[34:37], v[74:77]
	v_mfma_f32_16x16x32_bf16 v[70:73], v[6:9], v[34:37], v[98:101]
	v_mfma_f32_16x16x32_bf16 v[74:77], v[2:5], v[38:41], v[102:105]
	v_mfma_f32_16x16x32_bf16 v[78:81], v[2:5], v[34:37], v[106:109]
	global_load_dwordx4 v[34:37], v[112:113], off offset:192
	global_load_dwordx4 v[38:41], v[152:153], off offset:192
	global_load_dwordx4 v[42:45], v[154:155], off offset:192
	global_load_dwordx4 v[98:101], v[112:113], off offset:128
	global_load_dwordx4 v[102:105], v[152:153], off offset:128
	global_load_dwordx4 v[106:109], v[154:155], off offset:128
	global_load_dwordx4 v[46:49], v[110:111], off offset:192
	s_nop 0
	global_load_dwordx4 v[110:113], v[110:111], off offset:128
	s_nop 0
	global_load_dwordx4 v[2:5], v[156:157], off offset:192
	global_load_dwordx4 v[6:9], v[156:157], off offset:128
	global_load_dwordx4 v[10:13], v[156:157], off offset:64
	global_load_dwordx4 v[14:17], v[156:157], off
	v_mul_lo_u32 v154, v159, 12
	v_ashrrev_i32_e32 v155, 31, v154
	v_lshl_add_u64 v[152:153], v[154:155], 0, v[130:131]
	v_add_u32_e32 v154, 6, v154
	v_ashrrev_i32_e32 v155, 31, v154
	v_lshl_add_u64 v[130:131], v[154:155], 0, v[130:131]
	v_lshlrev_b64 v[152:153], 13, v[152:153]
	v_lshlrev_b32_e32 v156, 7, v158
	v_lshlrev_b64 v[130:131], 13, v[130:131]
	v_lshl_add_u64 v[160:161], v[132:133], 0, v[152:153]
	v_mov_b32_e32 v157, v1
	v_or_b32_e32 v172, 0x1000, v156
	v_or_b32_e32 v174, 0x1800, v156
	v_lshl_add_u64 v[130:131], v[132:133], 0, v[130:131]
	v_lshl_add_u64 v[152:153], v[160:161], 0, v[156:157]
	v_lshl_add_u64 v[158:159], v[160:161], 0, v[172:173]
	v_lshl_add_u64 v[162:163], v[160:161], 0, v[174:175]
	v_lshl_add_u64 v[154:155], v[130:131], 0, v[156:157]
	v_lshl_add_u64 v[156:157], v[130:131], 0, v[172:173]
	v_lshl_add_u64 v[160:161], v[130:131], 0, v[174:175]
	v_mfma_f32_16x16x32_bf16 v[130:133], v[126:129], v[30:33], 0
	v_or_b32_e32 v173, 64, v0
	v_or_b32_e32 v172, 0x44, v0
	s_waitcnt vmcnt(0)
	v_mfma_f32_16x16x32_bf16 v[126:129], v[126:129], v[26:29], 0
	v_mfma_f32_16x16x32_bf16 v[130:133], v[122:125], v[22:25], v[130:133]
	v_mfma_f32_16x16x32_bf16 v[122:125], v[122:125], v[18:21], v[126:129]
	v_mfma_f32_16x16x32_bf16 v[126:129], v[118:121], v[30:33], 0
	v_mfma_f32_16x16x32_bf16 v[118:121], v[118:121], v[26:29], 0
	v_mfma_f32_16x16x32_bf16 v[126:129], v[114:117], v[22:25], v[126:129]
	v_mfma_f32_16x16x32_bf16 v[114:117], v[114:117], v[18:21], v[118:121]
	s_nop 5
	v_sub_u32_e32 v118, v168, v173
	v_cvt_f32_u32_e32 v119, v118
	v_cmp_lt_i32_e32 vcc, -1, v118
	v_mul_f32_e32 v119, v169, v119
	v_exp_f32_e32 v119, v119
	s_nop 0
	v_cndmask_b32_e32 v119, 0, v119, vcc
	v_cmp_gt_i32_e32 vcc, 1, v118
	v_sub_u32_e32 v118, 0, v118
	v_cvt_f32_u32_e32 v118, v118
	v_mul_f32_e32 v118, v170, v118
	v_exp_f32_e32 v118, v118
	s_nop 0
	v_cndmask_b32_e32 v118, 0, v118, vcc
	v_add_f32_e32 v118, v119, v118
	v_mul_f32_e32 v118, v118, v130
	v_or_b32_e32 v130, 0x41, v0
	v_sub_u32_e32 v119, v168, v130
	v_cvt_f32_u32_e32 v120, v119
	v_cmp_lt_i32_e32 vcc, -1, v119
	v_mul_f32_e32 v120, v169, v120
	v_exp_f32_e32 v120, v120
	s_nop 0
	v_cndmask_b32_e32 v120, 0, v120, vcc
	v_cmp_gt_i32_e32 vcc, 1, v119
	v_sub_u32_e32 v119, 0, v119
	v_cvt_f32_u32_e32 v119, v119
	v_mul_f32_e32 v119, v170, v119
	v_exp_f32_e32 v119, v119
	s_nop 0
	v_cndmask_b32_e32 v119, 0, v119, vcc
	v_add_f32_e32 v119, v120, v119
	v_mul_f32_e32 v119, v119, v131
	v_or_b32_e32 v131, 0x42, v0
	v_sub_u32_e32 v120, v168, v131
	v_cvt_f32_u32_e32 v121, v120
	v_cmp_lt_i32_e32 vcc, -1, v120
	v_cvt_pk_bf16_f32 v118, v118, v119
	v_mul_f32_e32 v121, v169, v121
	v_exp_f32_e32 v121, v121
	s_nop 0
	v_cndmask_b32_e32 v121, 0, v121, vcc
	v_cmp_gt_i32_e32 vcc, 1, v120
	v_sub_u32_e32 v120, 0, v120
	v_cvt_f32_u32_e32 v120, v120
	v_mul_f32_e32 v120, v170, v120
	v_exp_f32_e32 v120, v120
	s_nop 0
	v_cndmask_b32_e32 v120, 0, v120, vcc
	v_add_f32_e32 v120, v121, v120
	v_mul_f32_e32 v120, v120, v132
	v_or_b32_e32 v132, 0x43, v0
	v_sub_u32_e32 v121, v168, v132
	v_cvt_f32_u32_e32 v174, v121
	v_cmp_lt_i32_e32 vcc, -1, v121
	v_mul_f32_e32 v174, v169, v174
	v_exp_f32_e32 v174, v174
	s_nop 0
	v_cndmask_b32_e32 v174, 0, v174, vcc
	v_cmp_gt_i32_e32 vcc, 1, v121
	v_sub_u32_e32 v121, 0, v121
	v_cvt_f32_u32_e32 v121, v121
	v_mul_f32_e32 v121, v170, v121
	v_exp_f32_e32 v121, v121
	s_nop 0
	v_cndmask_b32_e32 v121, 0, v121, vcc
	v_add_f32_e32 v121, v174, v121
	v_mul_f32_e32 v121, v121, v133
	v_sub_u32_e32 v133, v168, v172
	v_cvt_f32_u32_e32 v174, v133
	v_cmp_lt_i32_e32 vcc, -1, v133
	v_cvt_pk_bf16_f32 v119, v120, v121
	v_mul_f32_e32 v174, v169, v174
	v_exp_f32_e32 v174, v174
	s_nop 0
	v_cndmask_b32_e32 v174, 0, v174, vcc
	v_cmp_gt_i32_e32 vcc, 1, v133
	v_sub_u32_e32 v133, 0, v133
	v_cvt_f32_u32_e32 v133, v133
	v_mul_f32_e32 v133, v170, v133
	v_exp_f32_e32 v133, v133
	s_nop 0
	v_cndmask_b32_e32 v133, 0, v133, vcc
	v_add_f32_e32 v133, v174, v133
	v_mul_f32_e32 v133, v133, v126
	v_or_b32_e32 v126, 0x45, v0
	v_sub_u32_e32 v174, v168, v126
	v_cvt_f32_u32_e32 v175, v174
	v_cmp_lt_i32_e32 vcc, -1, v174
	v_mul_f32_e32 v175, v169, v175
	v_exp_f32_e32 v175, v175
	s_nop 0
	v_cndmask_b32_e32 v175, 0, v175, vcc
	v_cmp_gt_i32_e32 vcc, 1, v174
	v_sub_u32_e32 v174, 0, v174
	v_cvt_f32_u32_e32 v174, v174
	v_mul_f32_e32 v174, v170, v174
	v_exp_f32_e32 v174, v174
	s_nop 0
	v_cndmask_b32_e32 v174, 0, v174, vcc
	v_add_f32_e32 v174, v175, v174
	v_mul_f32_e32 v174, v174, v127
	v_or_b32_e32 v127, 0x46, v0
	v_sub_u32_e32 v175, v168, v127
	v_cvt_f32_u32_e32 v176, v175
	v_cmp_lt_i32_e32 vcc, -1, v175
	v_cvt_pk_bf16_f32 v120, v133, v174
	v_mul_f32_e32 v176, v169, v176
	v_exp_f32_e32 v176, v176
	s_nop 0
	v_cndmask_b32_e32 v176, 0, v176, vcc
	v_cmp_gt_i32_e32 vcc, 1, v175
	v_sub_u32_e32 v175, 0, v175
	v_cvt_f32_u32_e32 v175, v175
	v_mul_f32_e32 v175, v170, v175
	v_exp_f32_e32 v175, v175
	s_nop 0
	v_cndmask_b32_e32 v175, 0, v175, vcc
	v_add_f32_e32 v175, v176, v175
	v_mul_f32_e32 v175, v175, v128
	v_or_b32_e32 v128, 0x47, v0
	v_sub_u32_e32 v176, v168, v128
	v_cvt_f32_u32_e32 v177, v176
	v_cmp_lt_i32_e32 vcc, -1, v176
	v_mul_f32_e32 v177, v169, v177
	v_exp_f32_e32 v177, v177
	s_nop 0
	v_cndmask_b32_e32 v177, 0, v177, vcc
	v_cmp_gt_i32_e32 vcc, 1, v176
	v_sub_u32_e32 v176, 0, v176
	v_cvt_f32_u32_e32 v176, v176
	v_mul_f32_e32 v176, v170, v176
	v_exp_f32_e32 v176, v176
	s_nop 0
	v_cndmask_b32_e32 v176, 0, v176, vcc
	v_add_f32_e32 v176, v177, v176
	v_mul_f32_e32 v129, v176, v129
	v_cvt_pk_bf16_f32 v121, v175, v129
	v_sub_u32_e32 v129, v171, v173
	v_cvt_f32_u32_e32 v133, v129
	v_cmp_lt_i32_e32 vcc, -1, v129
	v_mfma_f32_16x16x32_bf16 v[74:77], v[98:101], v[118:121], v[74:77]
	v_mul_f32_e32 v133, v169, v133
	v_exp_f32_e32 v133, v133
	v_mfma_f32_16x16x32_bf16 v[66:69], v[102:105], v[118:121], v[66:69]
	v_cndmask_b32_e32 v133, 0, v133, vcc
	v_cmp_gt_i32_e32 vcc, 1, v129
	v_sub_u32_e32 v129, 0, v129
	v_cvt_f32_u32_e32 v129, v129
	v_mfma_f32_16x16x32_bf16 v[58:61], v[106:109], v[118:121], v[58:61]
	v_mul_f32_e32 v129, v170, v129
	v_exp_f32_e32 v129, v129
	v_mfma_f32_16x16x32_bf16 v[50:53], v[110:113], v[118:121], v[50:53]
	v_cndmask_b32_e32 v129, 0, v129, vcc
	v_add_f32_e32 v129, v133, v129
	v_mul_f32_e32 v122, v129, v122
	v_sub_u32_e32 v129, v171, v130
	v_cvt_f32_u32_e32 v130, v129
	v_cmp_lt_i32_e32 vcc, -1, v129
	v_mul_f32_e32 v130, v169, v130
	v_exp_f32_e32 v130, v130
	s_nop 0
	v_cndmask_b32_e32 v130, 0, v130, vcc
	v_cmp_gt_i32_e32 vcc, 1, v129
	v_sub_u32_e32 v129, 0, v129
	v_cvt_f32_u32_e32 v129, v129
	v_mul_f32_e32 v129, v170, v129
	v_exp_f32_e32 v129, v129
	s_nop 0
	v_cndmask_b32_e32 v129, 0, v129, vcc
	v_add_f32_e32 v129, v130, v129
	v_mul_f32_e32 v123, v129, v123
	v_sub_u32_e32 v129, v171, v131
	v_cvt_f32_u32_e32 v130, v129
	v_cmp_lt_i32_e32 vcc, -1, v129
	v_mul_f32_e32 v130, v169, v130
	v_exp_f32_e32 v130, v130
	s_nop 0
	v_cndmask_b32_e32 v130, 0, v130, vcc
	v_cmp_gt_i32_e32 vcc, 1, v129
	v_sub_u32_e32 v129, 0, v129
	v_cvt_f32_u32_e32 v129, v129
	v_mul_f32_e32 v129, v170, v129
	v_exp_f32_e32 v129, v129
	s_nop 0
	v_cndmask_b32_e32 v129, 0, v129, vcc
	v_add_f32_e32 v129, v130, v129
	v_mul_f32_e32 v124, v129, v124
	v_sub_u32_e32 v129, v171, v132
	v_cvt_f32_u32_e32 v130, v129
	v_cmp_lt_i32_e32 vcc, -1, v129
	v_mul_f32_e32 v130, v169, v130
	v_exp_f32_e32 v130, v130
	s_nop 0
	v_cndmask_b32_e32 v130, 0, v130, vcc
	v_cmp_gt_i32_e32 vcc, 1, v129
	v_sub_u32_e32 v129, 0, v129
	v_cvt_f32_u32_e32 v129, v129
	v_mul_f32_e32 v129, v170, v129
	v_exp_f32_e32 v129, v129
	s_nop 0
	v_cndmask_b32_e32 v129, 0, v129, vcc
	v_add_f32_e32 v129, v130, v129
	v_mul_f32_e32 v125, v129, v125
	v_sub_u32_e32 v129, v171, v172
	v_cvt_f32_u32_e32 v130, v129
	v_cmp_lt_i32_e32 vcc, -1, v129
	v_mul_f32_e32 v130, v169, v130
	v_exp_f32_e32 v130, v130
	s_nop 0
	v_cndmask_b32_e32 v130, 0, v130, vcc
	v_cmp_gt_i32_e32 vcc, 1, v129
	v_sub_u32_e32 v129, 0, v129
	v_cvt_f32_u32_e32 v129, v129
	v_mul_f32_e32 v129, v170, v129
	v_exp_f32_e32 v129, v129
	s_nop 0
	v_cndmask_b32_e32 v129, 0, v129, vcc
	v_add_f32_e32 v129, v130, v129
	v_mul_f32_e32 v129, v129, v114
	v_sub_u32_e32 v114, v171, v126
	v_cvt_f32_u32_e32 v126, v114
	v_cmp_lt_i32_e32 vcc, -1, v114
	v_mul_f32_e32 v126, v169, v126
	v_exp_f32_e32 v126, v126
	s_nop 0
	v_cndmask_b32_e32 v126, 0, v126, vcc
	v_cmp_gt_i32_e32 vcc, 1, v114
	v_sub_u32_e32 v114, 0, v114
	v_cvt_f32_u32_e32 v114, v114
	v_mul_f32_e32 v114, v170, v114
	v_exp_f32_e32 v114, v114
	s_nop 0
	v_cndmask_b32_e32 v114, 0, v114, vcc
	v_add_f32_e32 v114, v126, v114
	v_mul_f32_e32 v126, v114, v115
	v_sub_u32_e32 v114, v171, v127
	v_cvt_f32_u32_e32 v115, v114
	v_cmp_lt_i32_e32 vcc, -1, v114
	v_mul_f32_e32 v115, v169, v115
	v_exp_f32_e32 v115, v115
	s_nop 0
	v_cndmask_b32_e32 v115, 0, v115, vcc
	v_cmp_gt_i32_e32 vcc, 1, v114
	v_sub_u32_e32 v114, 0, v114
	v_cvt_f32_u32_e32 v114, v114
	v_mul_f32_e32 v114, v170, v114
	v_exp_f32_e32 v114, v114
	s_nop 0
	v_cndmask_b32_e32 v114, 0, v114, vcc
	v_add_f32_e32 v114, v115, v114
	v_mul_f32_e32 v127, v114, v116
	v_sub_u32_e32 v114, v171, v128
	v_cvt_f32_u32_e32 v115, v114
	v_cmp_lt_i32_e32 vcc, -1, v114
	v_cvt_pk_bf16_f32 v116, v129, v126
	v_mul_f32_e32 v115, v169, v115
	v_exp_f32_e32 v115, v115
	s_nop 0
	v_cndmask_b32_e32 v115, 0, v115, vcc
	v_cmp_gt_i32_e32 vcc, 1, v114
	v_sub_u32_e32 v114, 0, v114
	v_cvt_f32_u32_e32 v114, v114
	v_mul_f32_e32 v114, v170, v114
	v_exp_f32_e32 v114, v114
	s_nop 0
	v_cndmask_b32_e32 v114, 0, v114, vcc
	v_add_f32_e32 v114, v115, v114
	v_mul_f32_e32 v117, v114, v117
	v_cvt_pk_bf16_f32 v114, v122, v123
	v_cvt_pk_bf16_f32 v115, v124, v125
	v_cvt_pk_bf16_f32 v117, v127, v117
	s_nop 1
	v_mfma_f32_16x16x32_bf16 v[78:81], v[98:101], v[114:117], v[78:81]
	v_mfma_f32_16x16x32_bf16 v[98:101], v[94:97], v[30:33], 0
	v_mfma_f32_16x16x32_bf16 v[94:97], v[94:97], v[26:29], 0
	v_mfma_f32_16x16x32_bf16 v[98:101], v[90:93], v[22:25], v[98:101]
	v_mfma_f32_16x16x32_bf16 v[90:93], v[90:93], v[18:21], v[94:97]
	v_mfma_f32_16x16x32_bf16 v[94:97], v[86:89], v[30:33], 0
	v_mfma_f32_16x16x32_bf16 v[86:89], v[86:89], v[26:29], 0
	v_mfma_f32_16x16x32_bf16 v[70:73], v[102:105], v[114:117], v[70:73]
	v_or_b32_e32 v103, 0x60, v0
	v_or_b32_e32 v102, 0x64, v0
	v_mfma_f32_16x16x32_bf16 v[94:97], v[82:85], v[22:25], v[94:97]
	v_mfma_f32_16x16x32_bf16 v[82:85], v[82:85], v[18:21], v[86:89]
	s_nop 2
	v_sub_u32_e32 v86, v168, v103
	v_cvt_f32_u32_e32 v87, v86
	v_cmp_lt_i32_e32 vcc, -1, v86
	v_mfma_f32_16x16x32_bf16 v[62:65], v[106:109], v[114:117], v[62:65]
	v_mul_f32_e32 v87, v169, v87
	v_exp_f32_e32 v87, v87
	v_mfma_f32_16x16x32_bf16 v[54:57], v[110:113], v[114:117], v[54:57]
	v_cndmask_b32_e32 v87, 0, v87, vcc
	v_cmp_gt_i32_e32 vcc, 1, v86
	v_sub_u32_e32 v86, 0, v86
	v_cvt_f32_u32_e32 v86, v86
	v_mul_f32_e32 v86, v170, v86
	v_exp_f32_e32 v86, v86
	s_nop 0
	v_cndmask_b32_e32 v86, 0, v86, vcc
	v_add_f32_e32 v86, v87, v86
	v_mul_f32_e32 v86, v86, v98
	v_or_b32_e32 v98, 0x61, v0
	v_sub_u32_e32 v87, v168, v98
	v_cvt_f32_u32_e32 v88, v87
	v_cmp_lt_i32_e32 vcc, -1, v87
	v_mul_f32_e32 v88, v169, v88
	v_exp_f32_e32 v88, v88
	s_nop 0
	v_cndmask_b32_e32 v88, 0, v88, vcc
	v_cmp_gt_i32_e32 vcc, 1, v87
	v_sub_u32_e32 v87, 0, v87
	v_cvt_f32_u32_e32 v87, v87
	v_mul_f32_e32 v87, v170, v87
	v_exp_f32_e32 v87, v87
	s_nop 0
	v_cndmask_b32_e32 v87, 0, v87, vcc
	v_add_f32_e32 v87, v88, v87
	v_mul_f32_e32 v87, v87, v99
	v_or_b32_e32 v99, 0x62, v0
	v_sub_u32_e32 v88, v168, v99
	v_cvt_f32_u32_e32 v89, v88
	v_cmp_lt_i32_e32 vcc, -1, v88
	v_cvt_pk_bf16_f32 v86, v86, v87
	v_mul_f32_e32 v89, v169, v89
	v_exp_f32_e32 v89, v89
	s_nop 0
	v_cndmask_b32_e32 v89, 0, v89, vcc
	v_cmp_gt_i32_e32 vcc, 1, v88
	v_sub_u32_e32 v88, 0, v88
	v_cvt_f32_u32_e32 v88, v88
	v_mul_f32_e32 v88, v170, v88
	v_exp_f32_e32 v88, v88
	s_nop 0
	v_cndmask_b32_e32 v88, 0, v88, vcc
	v_add_f32_e32 v88, v89, v88
	v_mul_f32_e32 v88, v88, v100
	v_or_b32_e32 v100, 0x63, v0
	v_sub_u32_e32 v89, v168, v100
	v_cvt_f32_u32_e32 v104, v89
	v_cmp_lt_i32_e32 vcc, -1, v89
	v_mul_f32_e32 v104, v169, v104
	v_exp_f32_e32 v104, v104
	s_nop 0
	v_cndmask_b32_e32 v104, 0, v104, vcc
	v_cmp_gt_i32_e32 vcc, 1, v89
	v_sub_u32_e32 v89, 0, v89
	v_cvt_f32_u32_e32 v89, v89
	v_mul_f32_e32 v89, v170, v89
	v_exp_f32_e32 v89, v89
	s_nop 0
	v_cndmask_b32_e32 v89, 0, v89, vcc
	v_add_f32_e32 v89, v104, v89
	v_mul_f32_e32 v89, v89, v101
	v_sub_u32_e32 v101, v168, v102
	v_cvt_f32_u32_e32 v104, v101
	v_cmp_lt_i32_e32 vcc, -1, v101
	v_cvt_pk_bf16_f32 v87, v88, v89
	v_mul_f32_e32 v104, v169, v104
	v_exp_f32_e32 v104, v104
	s_nop 0
	v_cndmask_b32_e32 v104, 0, v104, vcc
	v_cmp_gt_i32_e32 vcc, 1, v101
	v_sub_u32_e32 v101, 0, v101
	v_cvt_f32_u32_e32 v101, v101
	v_mul_f32_e32 v101, v170, v101
	v_exp_f32_e32 v101, v101
	s_nop 0
	v_cndmask_b32_e32 v101, 0, v101, vcc
	v_add_f32_e32 v101, v104, v101
	v_mul_f32_e32 v101, v101, v94
	v_or_b32_e32 v94, 0x65, v0
	v_sub_u32_e32 v104, v168, v94
	v_cvt_f32_u32_e32 v105, v104
	v_cmp_lt_i32_e32 vcc, -1, v104
	v_sub_u32_e32 v94, v171, v94
	v_mul_f32_e32 v105, v169, v105
	v_exp_f32_e32 v105, v105
	s_nop 0
	v_cndmask_b32_e32 v105, 0, v105, vcc
	v_cmp_gt_i32_e32 vcc, 1, v104
	v_sub_u32_e32 v104, 0, v104
	v_cvt_f32_u32_e32 v104, v104
	v_mul_f32_e32 v104, v170, v104
	v_exp_f32_e32 v104, v104
	s_nop 0
	v_cndmask_b32_e32 v104, 0, v104, vcc
	v_add_f32_e32 v104, v105, v104
	v_mul_f32_e32 v104, v104, v95
	v_or_b32_e32 v95, 0x66, v0
	v_sub_u32_e32 v105, v168, v95
	v_cvt_f32_u32_e32 v106, v105
	v_cmp_lt_i32_e32 vcc, -1, v105
	v_cvt_pk_bf16_f32 v88, v101, v104
	v_mul_f32_e32 v106, v169, v106
	v_exp_f32_e32 v106, v106
	s_nop 0
	v_cndmask_b32_e32 v106, 0, v106, vcc
	v_cmp_gt_i32_e32 vcc, 1, v105
	v_sub_u32_e32 v105, 0, v105
	v_cvt_f32_u32_e32 v105, v105
	v_mul_f32_e32 v105, v170, v105
	v_exp_f32_e32 v105, v105
	s_nop 0
	v_cndmask_b32_e32 v105, 0, v105, vcc
	v_add_f32_e32 v105, v106, v105
	v_mul_f32_e32 v105, v105, v96
	v_or_b32_e32 v96, 0x67, v0
	v_sub_u32_e32 v106, v168, v96
	v_cvt_f32_u32_e32 v107, v106
	v_cmp_lt_i32_e32 vcc, -1, v106
	v_mul_f32_e32 v107, v169, v107
	v_exp_f32_e32 v107, v107
	s_nop 0
	v_cndmask_b32_e32 v107, 0, v107, vcc
	v_cmp_gt_i32_e32 vcc, 1, v106
	v_sub_u32_e32 v106, 0, v106
	v_cvt_f32_u32_e32 v106, v106
	v_mul_f32_e32 v106, v170, v106
	v_exp_f32_e32 v106, v106
	s_nop 0
	v_cndmask_b32_e32 v106, 0, v106, vcc
	v_add_f32_e32 v106, v107, v106
	v_mul_f32_e32 v97, v106, v97
	v_cvt_pk_bf16_f32 v89, v105, v97
	v_sub_u32_e32 v97, v171, v103
	v_cvt_f32_u32_e32 v101, v97
	v_cmp_lt_i32_e32 vcc, -1, v97
	v_mfma_f32_16x16x32_bf16 v[50:53], v[46:49], v[86:89], v[50:53]
	v_mul_f32_e32 v101, v169, v101
	v_exp_f32_e32 v101, v101
	v_mfma_f32_16x16x32_bf16 v[58:61], v[42:45], v[86:89], v[58:61]
	v_cndmask_b32_e32 v101, 0, v101, vcc
	v_cmp_gt_i32_e32 vcc, 1, v97
	v_sub_u32_e32 v97, 0, v97
	v_cvt_f32_u32_e32 v97, v97
	v_mul_f32_e32 v97, v170, v97
	v_exp_f32_e32 v97, v97
	s_nop 0
	v_cndmask_b32_e32 v97, 0, v97, vcc
	v_add_f32_e32 v97, v101, v97
	v_mul_f32_e32 v90, v97, v90
	v_sub_u32_e32 v97, v171, v98
	v_cvt_f32_u32_e32 v98, v97
	v_cmp_lt_i32_e32 vcc, -1, v97
	v_mul_f32_e32 v98, v169, v98
	v_exp_f32_e32 v98, v98
	s_nop 0
	v_cndmask_b32_e32 v98, 0, v98, vcc
	v_cmp_gt_i32_e32 vcc, 1, v97
	v_sub_u32_e32 v97, 0, v97
	v_cvt_f32_u32_e32 v97, v97
	v_mul_f32_e32 v97, v170, v97
	v_exp_f32_e32 v97, v97
	s_nop 0
	v_cndmask_b32_e32 v97, 0, v97, vcc
	v_add_f32_e32 v97, v98, v97
	v_mul_f32_e32 v91, v97, v91
	v_sub_u32_e32 v97, v171, v99
	v_cvt_f32_u32_e32 v98, v97
	v_cmp_lt_i32_e32 vcc, -1, v97
	v_cvt_pk_bf16_f32 v90, v90, v91
	v_mul_f32_e32 v98, v169, v98
	v_exp_f32_e32 v98, v98
	s_nop 0
	v_cndmask_b32_e32 v98, 0, v98, vcc
	v_cmp_gt_i32_e32 vcc, 1, v97
	v_sub_u32_e32 v97, 0, v97
	v_cvt_f32_u32_e32 v97, v97
	v_mul_f32_e32 v97, v170, v97
	v_exp_f32_e32 v97, v97
	s_nop 0
	v_cndmask_b32_e32 v97, 0, v97, vcc
	v_add_f32_e32 v97, v98, v97
	v_mul_f32_e32 v92, v97, v92
	v_sub_u32_e32 v97, v171, v100
	v_cvt_f32_u32_e32 v98, v97
	v_cmp_lt_i32_e32 vcc, -1, v97
	v_mul_f32_e32 v98, v169, v98
	v_exp_f32_e32 v98, v98
	s_nop 0
	v_cndmask_b32_e32 v98, 0, v98, vcc
	v_cmp_gt_i32_e32 vcc, 1, v97
	v_sub_u32_e32 v97, 0, v97
	v_cvt_f32_u32_e32 v97, v97
	v_mul_f32_e32 v97, v170, v97
	v_exp_f32_e32 v97, v97
	s_nop 0
	v_cndmask_b32_e32 v97, 0, v97, vcc
	v_add_f32_e32 v97, v98, v97
	v_mul_f32_e32 v93, v97, v93
	v_sub_u32_e32 v97, v171, v102
	v_cvt_f32_u32_e32 v98, v97
	v_cmp_lt_i32_e32 vcc, -1, v97
	v_cvt_pk_bf16_f32 v91, v92, v93
	v_mul_f32_e32 v98, v169, v98
	v_exp_f32_e32 v98, v98
	s_nop 0
	v_cndmask_b32_e32 v98, 0, v98, vcc
	v_cmp_gt_i32_e32 vcc, 1, v97
	v_sub_u32_e32 v97, 0, v97
	v_cvt_f32_u32_e32 v97, v97
	v_mul_f32_e32 v97, v170, v97
	v_exp_f32_e32 v97, v97
	s_nop 0
	v_cndmask_b32_e32 v97, 0, v97, vcc
	v_add_f32_e32 v97, v98, v97
	v_mul_f32_e32 v82, v97, v82
	v_cvt_f32_u32_e32 v97, v94
	v_cmp_lt_i32_e32 vcc, -1, v94
	v_mul_f32_e32 v97, v169, v97
	v_exp_f32_e32 v97, v97
	s_nop 0
	v_cndmask_b32_e32 v97, 0, v97, vcc
	v_cmp_gt_i32_e32 vcc, 1, v94
	v_sub_u32_e32 v94, 0, v94
	v_cvt_f32_u32_e32 v94, v94
	v_mul_f32_e32 v94, v170, v94
	v_exp_f32_e32 v94, v94
	s_nop 0
	v_cndmask_b32_e32 v94, 0, v94, vcc
	v_add_f32_e32 v94, v97, v94
	v_mul_f32_e32 v83, v94, v83
	v_sub_u32_e32 v94, v171, v95
	v_cvt_f32_u32_e32 v95, v94
	v_cmp_lt_i32_e32 vcc, -1, v94
	v_cvt_pk_bf16_f32 v92, v82, v83
	v_mul_f32_e32 v95, v169, v95
	v_exp_f32_e32 v95, v95
	s_nop 0
	v_cndmask_b32_e32 v95, 0, v95, vcc
	v_cmp_gt_i32_e32 vcc, 1, v94
	v_sub_u32_e32 v94, 0, v94
	v_cvt_f32_u32_e32 v94, v94
	v_mul_f32_e32 v94, v170, v94
	v_exp_f32_e32 v94, v94
	s_nop 0
	v_cndmask_b32_e32 v94, 0, v94, vcc
	v_add_f32_e32 v94, v95, v94
	v_mul_f32_e32 v84, v94, v84
	v_sub_u32_e32 v94, v171, v96
	v_cvt_f32_u32_e32 v95, v94
	v_cmp_lt_i32_e32 vcc, -1, v94
	v_mul_f32_e32 v95, v169, v95
	v_exp_f32_e32 v95, v95
	s_nop 0
	v_cndmask_b32_e32 v95, 0, v95, vcc
	v_cmp_gt_i32_e32 vcc, 1, v94
	v_sub_u32_e32 v94, 0, v94
	v_cvt_f32_u32_e32 v94, v94
	v_mul_f32_e32 v94, v170, v94
	v_exp_f32_e32 v94, v94
	s_nop 0
	v_cndmask_b32_e32 v94, 0, v94, vcc
	v_add_f32_e32 v94, v95, v94
	v_mul_f32_e32 v85, v94, v85
	v_cvt_pk_bf16_f32 v93, v84, v85
	v_cmp_lt_i32_e32 vcc, v210, v208
	v_mfma_f32_16x16x32_bf16 v[54:57], v[46:49], v[90:93], v[54:57]
	v_mfma_f32_16x16x32_bf16 v[62:65], v[42:45], v[90:93], v[62:65]
	v_mfma_f32_16x16x32_bf16 v[46:49], v[38:41], v[86:89], v[66:69]
	v_mfma_f32_16x16x32_bf16 v[66:69], v[38:41], v[90:93], v[70:73]
	v_mfma_f32_16x16x32_bf16 v[38:41], v[34:37], v[86:89], v[74:77]
	v_mfma_f32_16x16x32_bf16 v[70:73], v[34:37], v[90:93], v[78:81]
	global_load_dwordx4 v[34:37], v[162:163], off offset:64
	global_load_dwordx4 v[42:45], v[162:163], off
	global_load_dwordx4 v[74:77], v[158:159], off offset:64
	global_load_dwordx4 v[78:81], v[158:159], off
	global_load_dwordx4 v[82:85], v[152:153], off offset:2112
	global_load_dwordx4 v[86:89], v[152:153], off offset:2048
	global_load_dwordx4 v[90:93], v[152:153], off offset:64
	global_load_dwordx4 v[94:97], v[152:153], off
	global_load_dwordx4 v[98:101], v[160:161], off offset:64
	global_load_dwordx4 v[102:105], v[160:161], off
	global_load_dwordx4 v[106:109], v[156:157], off offset:64
	global_load_dwordx4 v[110:113], v[156:157], off
	global_load_dwordx4 v[114:117], v[154:155], off offset:2112
	global_load_dwordx4 v[118:121], v[154:155], off offset:2048
	global_load_dwordx4 v[122:125], v[154:155], off offset:64
	global_load_dwordx4 v[126:129], v[154:155], off
	s_waitcnt vmcnt(0)
	s_nop 0
	v_mfma_f32_16x16x32_bf16 v[130:133], v[94:97], v[30:33], 0
	v_mfma_f32_16x16x32_bf16 v[94:97], v[94:97], v[26:29], 0
	v_mfma_f32_16x16x32_bf16 v[130:133], v[90:93], v[22:25], v[130:133]
	v_mfma_f32_16x16x32_bf16 v[90:93], v[90:93], v[18:21], v[94:97]
	v_mfma_f32_16x16x32_bf16 v[94:97], v[86:89], v[30:33], 0
	v_mfma_f32_16x16x32_bf16 v[86:89], v[86:89], v[26:29], 0
	v_mfma_f32_16x16x32_bf16 v[94:97], v[82:85], v[22:25], v[94:97]
	v_mfma_f32_16x16x32_bf16 v[82:85], v[82:85], v[18:21], v[86:89]
	v_mfma_f32_16x16x32_bf16 v[86:89], v[78:81], v[30:33], 0
	v_mfma_f32_16x16x32_bf16 v[78:81], v[78:81], v[26:29], 0
	v_mfma_f32_16x16x32_bf16 v[86:89], v[74:77], v[22:25], v[86:89]
	v_mfma_f32_16x16x32_bf16 v[74:77], v[74:77], v[18:21], v[78:81]
	v_mfma_f32_16x16x32_bf16 v[78:81], v[42:45], v[30:33], 0
	v_mfma_f32_16x16x32_bf16 v[42:45], v[42:45], v[26:29], 0
	v_mfma_f32_16x16x32_bf16 v[78:81], v[34:37], v[22:25], v[78:81]
	v_mfma_f32_16x16x32_bf16 v[152:155], v[34:37], v[18:21], v[42:45]
	v_mfma_f32_16x16x32_bf16 v[34:37], v[126:129], v[30:33], 0
	v_mfma_f32_16x16x32_bf16 v[42:45], v[126:129], v[26:29], 0
	v_mfma_f32_16x16x32_bf16 v[126:129], v[122:125], v[22:25], v[34:37]
	v_mfma_f32_16x16x32_bf16 v[122:125], v[122:125], v[18:21], v[42:45]
	v_mfma_f32_16x16x32_bf16 v[34:37], v[118:121], v[30:33], 0
	v_mfma_f32_16x16x32_bf16 v[42:45], v[118:121], v[26:29], 0
	v_mfma_f32_16x16x32_bf16 v[118:121], v[114:117], v[22:25], v[34:37]
	v_mfma_f32_16x16x32_bf16 v[114:117], v[114:117], v[18:21], v[42:45]
	v_mfma_f32_16x16x32_bf16 v[34:37], v[110:113], v[30:33], 0
	v_mfma_f32_16x16x32_bf16 v[42:45], v[110:113], v[26:29], 0
	v_mfma_f32_16x16x32_bf16 v[30:33], v[102:105], v[30:33], 0
	v_mfma_f32_16x16x32_bf16 v[26:29], v[102:105], v[26:29], 0
	v_mfma_f32_16x16x32_bf16 v[34:37], v[106:109], v[22:25], v[34:37]
	v_mfma_f32_16x16x32_bf16 v[106:109], v[106:109], v[18:21], v[42:45]
	v_mfma_f32_16x16x32_bf16 v[22:25], v[98:101], v[22:25], v[30:33]
	v_mfma_f32_16x16x32_bf16 v[98:101], v[98:101], v[18:21], v[26:29]
	v_sub_u32_e32 v18, 0x80, v171
	v_cvt_f32_ubyte0_e32 v18, v18
	v_mul_f32_e32 v18, v170, v18
	s_nop 0
	v_exp_f32_e32 v28, v18
	v_add_u32_e32 v18, 1, v168
	v_cvt_f32_ubyte0_e32 v18, v18
	v_mul_f32_e32 v18, v169, v18
	v_exp_f32_e32 v18, v18
	s_nop 0
	v_pk_fma_f32 v[20:21], v[18:19], v[80:81], v[40:41] op_sel_hi:[0,1,1]
	v_pk_fma_f32 v[26:27], v[18:19], v[78:79], v[38:39] op_sel_hi:[0,1,1]
	v_sub_u32_e32 v19, 0x80, v168
	v_cvt_f32_ubyte0_e32 v19, v19
	v_mul_f32_e32 v19, v170, v19
	v_exp_f32_e32 v30, v19
	s_nop 0
	v_pk_fma_f32 v[42:43], v[30:31], v[24:25], v[20:21] op_sel_hi:[0,1,1]
	v_pk_fma_f32 v[20:21], v[18:19], v[88:89], v[48:49] op_sel_hi:[0,1,1]
	v_pk_fma_f32 v[44:45], v[30:31], v[22:23], v[26:27] op_sel_hi:[0,1,1]
	v_pk_fma_f32 v[22:23], v[18:19], v[86:87], v[46:47] op_sel_hi:[0,1,1]
	v_pk_fma_f32 v[46:47], v[30:31], v[36:37], v[20:21] op_sel_hi:[0,1,1]
	v_pk_fma_f32 v[20:21], v[18:19], v[96:97], v[60:61] op_sel_hi:[0,1,1]
	v_pk_fma_f32 v[48:49], v[30:31], v[34:35], v[22:23] op_sel_hi:[0,1,1]
	v_pk_fma_f32 v[22:23], v[18:19], v[94:95], v[58:59] op_sel_hi:[0,1,1]
	v_pk_fma_f32 v[34:35], v[30:31], v[120:121], v[20:21] op_sel_hi:[0,1,1]
	v_pk_fma_f32 v[20:21], v[18:19], v[132:133], v[52:53] op_sel_hi:[0,1,1]
	v_pk_fma_f32 v[18:19], v[18:19], v[130:131], v[50:51] op_sel_hi:[0,1,1]
	v_pk_fma_f32 v[40:41], v[30:31], v[126:127], v[18:19] op_sel_hi:[0,1,1]
	v_add_u32_e32 v18, 17, v168
	v_cvt_f32_ubyte0_e32 v18, v18
	v_mul_f32_e32 v18, v169, v18
	v_exp_f32_e32 v18, v18
	v_pk_fma_f32 v[36:37], v[30:31], v[118:119], v[22:23] op_sel_hi:[0,1,1]
	v_pk_fma_f32 v[38:39], v[30:31], v[128:129], v[20:21] op_sel_hi:[0,1,1]
	v_and_b32_e32 v58, 0xffff0000, v151
	v_pk_fma_f32 v[26:27], v[18:19], v[154:155], v[72:73] op_sel_hi:[0,1,1]
	v_pk_fma_f32 v[50:51], v[18:19], v[152:153], v[70:71] op_sel_hi:[0,1,1]
	v_pk_fma_f32 v[30:31], v[18:19], v[76:77], v[68:69] op_sel_hi:[0,1,1]
	v_pk_fma_f32 v[32:33], v[18:19], v[74:75], v[66:67] op_sel_hi:[0,1,1]
	v_pk_fma_f32 v[20:21], v[18:19], v[84:85], v[64:65] op_sel_hi:[0,1,1]
	v_pk_fma_f32 v[52:53], v[18:19], v[82:83], v[62:63] op_sel_hi:[0,1,1]
	v_pk_fma_f32 v[22:23], v[18:19], v[92:93], v[56:57] op_sel_hi:[0,1,1]
	v_pk_fma_f32 v[18:19], v[18:19], v[90:91], v[54:55] op_sel_hi:[0,1,1]
	v_pk_fma_f32 v[22:23], v[28:29], v[124:125], v[22:23] op_sel_hi:[0,1,1]
	v_pk_fma_f32 v[24:25], v[28:29], v[122:123], v[18:19] op_sel_hi:[0,1,1]
	v_pk_fma_f32 v[18:19], v[28:29], v[116:117], v[20:21] op_sel_hi:[0,1,1]
	v_pk_fma_f32 v[20:21], v[28:29], v[114:115], v[52:53] op_sel_hi:[0,1,1]
	v_pk_fma_f32 v[30:31], v[28:29], v[108:109], v[30:31] op_sel_hi:[0,1,1]
	v_pk_fma_f32 v[32:33], v[28:29], v[106:107], v[32:33] op_sel_hi:[0,1,1]
	v_pk_fma_f32 v[26:27], v[28:29], v[100:101], v[26:27] op_sel_hi:[0,1,1]
	v_pk_fma_f32 v[28:29], v[28:29], v[98:99], v[50:51] op_sel_hi:[0,1,1]
	v_cndmask_b32_e32 v50, v207, v210, vcc
	v_cmp_lt_i32_e32 vcc, v209, v208
	v_lshlrev_b32_e32 v54, 2, v50
	v_mov_b32_e32 v51, v36
	v_cndmask_b32_e32 v50, v207, v209, vcc
	v_lshlrev_b32_e32 v55, 2, v50
	v_mov_b32_e32 v50, v40
	v_mov_b32_e32 v52, v41
	v_mov_b32_e32 v53, v37
	v_pk_add_f32 v[50:51], v[50:51], v[52:53]
	v_mov_b32_e32 v52, v38
	v_mov_b32_e32 v53, v34
	v_pk_add_f32 v[50:51], v[52:53], v[50:51]
	v_mov_b32_e32 v52, v39
	v_mov_b32_e32 v53, v35
	v_pk_add_f32 v[50:51], v[52:53], v[50:51]
	v_mov_b32_e32 v52, v49
	v_add_f32_e32 v50, 0, v50
	v_add_f32_e32 v56, v50, v51
	v_mov_b32_e32 v50, v48
	v_mov_b32_e32 v51, v44
	v_mov_b32_e32 v53, v45
	v_pk_add_f32 v[50:51], v[50:51], v[52:53]
	v_mov_b32_e32 v52, v46
	v_mov_b32_e32 v53, v42
	v_pk_add_f32 v[50:51], v[52:53], v[50:51]
	v_mov_b32_e32 v52, v47
	v_mov_b32_e32 v53, v43
	v_pk_add_f32 v[50:51], v[52:53], v[50:51]
	v_lshlrev_b32_e32 v57, 16, v151
	v_add_f32_e32 v50, v56, v50
	v_add_f32_e32 v50, v50, v51
	ds_bpermute_b32 v51, v54, v50
	s_waitcnt lgkmcnt(0)
	v_add_f32_e32 v50, v50, v51
	ds_bpermute_b32 v51, v55, v50
	s_waitcnt lgkmcnt(0)
	v_add_f32_e32 v51, v50, v51
	v_fmac_f32_e32 v41, 0xbc800000, v51
	v_fmamk_f32 v40, v51, 0xbc800000, v40
	v_mul_f32_e32 v56, v41, v41
	v_fmac_f32_e32 v56, v40, v40
	v_fmamk_f32 v38, v51, 0xbc800000, v38
	v_fmac_f32_e32 v56, v38, v38
	v_fmac_f32_e32 v39, 0xbc800000, v51
	v_fmac_f32_e32 v56, v39, v39
	v_fmamk_f32 v36, v51, 0xbc800000, v36
	v_fmac_f32_e32 v56, v36, v36
	v_fmac_f32_e32 v37, 0xbc800000, v51
	v_mul_f32_e32 v50, 0x3c800000, v51
	v_fmac_f32_e32 v56, v37, v37
	v_fmamk_f32 v34, v51, 0xbc800000, v34
	v_fmac_f32_e32 v56, v34, v34
	v_fmac_f32_e32 v35, 0xbc800000, v51
	v_pk_add_f32 v[48:49], v[48:49], v[50:51] op_sel_hi:[1,0] neg_lo:[0,1] neg_hi:[0,1]
	v_fmac_f32_e32 v56, v35, v35
	v_pk_mul_f32 v[52:53], v[48:49], v[48:49]
	s_nop 0
	v_add_f32_e32 v51, v52, v56
	v_add_f32_e32 v51, v53, v51
	v_pk_add_f32 v[46:47], v[46:47], v[50:51] op_sel_hi:[1,0] neg_lo:[0,1] neg_hi:[0,1]
	v_and_b32_e32 v56, 0xffff0000, v150
	v_pk_mul_f32 v[52:53], v[46:47], v[46:47]
	s_nop 0
	v_add_f32_e32 v51, v52, v51
	v_add_f32_e32 v51, v53, v51
	v_pk_add_f32 v[44:45], v[44:45], v[50:51] op_sel_hi:[1,0] neg_lo:[0,1] neg_hi:[0,1]
	s_nop 0
	v_pk_mul_f32 v[52:53], v[44:45], v[44:45]
	s_nop 0
	v_add_f32_e32 v51, v52, v51
	v_pk_add_f32 v[42:43], v[42:43], v[50:51] op_sel_hi:[1,0] neg_lo:[0,1] neg_hi:[0,1]
	v_add_f32_e32 v52, v53, v51
	v_pk_mul_f32 v[50:51], v[42:43], v[42:43]
	v_lshlrev_b32_e32 v53, 16, v150
	v_add_f32_e32 v50, v50, v52
	v_add_f32_e32 v50, v51, v50
	ds_bpermute_b32 v51, v54, v50
	s_waitcnt lgkmcnt(0)
	v_add_f32_e32 v50, v50, v51
	ds_bpermute_b32 v51, v55, v50
	s_waitcnt lgkmcnt(0)
	v_add_f32_e32 v50, v50, v51
	v_fmamk_f32 v50, v50, 0x3c800000, v203
	v_cmp_gt_f32_e32 vcc, s28, v50
	v_mul_f32_e32 v51, 0x4b800000, v50
	s_nop 0
	v_cndmask_b32_e32 v50, v50, v51, vcc
	v_rsq_f32_e32 v50, v50
	s_nop 0
	v_mul_f32_e32 v51, 0x45800000, v50
	v_cndmask_b32_e32 v52, v50, v51, vcc
	v_cmp_gt_i32_e32 vcc, s37, v167
	v_mul_f32_e32 v40, v40, v52
	v_mul_f32_e32 v38, v38, v52
	v_cndmask_b32_e64 v50, 3, 1, vcc
	v_add_u32_e32 v50, v50, v167
	v_ashrrev_i32_e32 v51, 31, v50
	v_lshlrev_b64 v[50:51], 11, v[50:51]
	v_mul_f32_e32 v40, v14, v40
	v_mul_f32_e32 v41, v41, v52
	v_mul_f32_e32 v38, v16, v38
	v_lshl_add_u64 v[50:51], s[8:9], 0, v[50:51]
	v_mul_f32_e32 v40, v40, v53
	v_mul_f32_e32 v41, v15, v41
	v_mul_f32_e32 v53, v38, v57
	v_mul_f32_e32 v38, v39, v52
	v_lshl_add_u64 v[50:51], v[50:51], 0, v[134:135]
	v_mul_f32_e32 v41, v41, v56
	v_mul_f32_e32 v38, v17, v38
	v_mul_f32_e32 v39, v38, v58
	v_cvt_pk_bf16_f32 v38, v40, v41
	v_lshl_add_u64 v[40:41], v[50:51], 0, v[0:1]
	v_lshl_add_u64 v[50:51], v[40:41], 0, s[54:55]
	v_add_co_u32_e32 v40, vcc, s34, v40
	v_mul_f32_e32 v36, v36, v52
	s_nop 0
	v_addc_co_u32_e32 v41, vcc, 0, v41, vcc
	v_mul_f32_e32 v34, v34, v52
	v_cvt_pk_bf16_f32 v39, v53, v39
	global_store_dwordx2 v[40:41], v[38:39], off offset:1280
	v_lshlrev_b32_e32 v38, 16, v148
	v_lshlrev_b32_e32 v40, 16, v149
	v_mul_f32_e32 v36, v10, v36
	v_mul_f32_e32 v34, v12, v34
	v_mul_f32_e32 v36, v36, v38
	v_mul_f32_e32 v38, v34, v40
	v_mul_f32_e32 v34, v35, v52
	v_and_b32_e32 v41, 0xffff0000, v149
	v_mul_f32_e32 v37, v37, v52
	v_mul_f32_e32 v34, v13, v34
	v_and_b32_e32 v39, 0xffff0000, v148
	v_mul_f32_e32 v37, v11, v37
	v_mul_f32_e32 v35, v34, v41
	v_mul_f32_e32 v37, v37, v39
	v_cvt_pk_bf16_f32 v34, v36, v37
	v_cvt_pk_bf16_f32 v35, v38, v35
	v_mul_f32_e32 v38, v48, v52
	global_store_dwordx2 v[50:51], v[34:35], off offset:32
	v_lshlrev_b32_e32 v34, 16, v146
	v_mul_f32_e32 v38, v6, v38
	v_mul_f32_e32 v34, v38, v34
	v_mul_f32_e32 v38, v49, v52
	v_and_b32_e32 v35, 0xffff0000, v146
	v_mul_f32_e32 v38, v7, v38
	v_mul_f32_e32 v35, v38, v35
	v_mul_f32_e32 v38, v46, v52
	v_lshlrev_b32_e32 v36, 16, v147
	v_mul_f32_e32 v38, v8, v38
	v_mul_f32_e32 v36, v38, v36
	v_mul_f32_e32 v38, v47, v52
	v_and_b32_e32 v37, 0xffff0000, v147
	v_mul_f32_e32 v38, v9, v38
	v_mul_f32_e32 v37, v38, v37
	v_cvt_pk_bf16_f32 v34, v34, v35
	v_mul_f32_e32 v38, v44, v52
	v_cvt_pk_bf16_f32 v35, v36, v37
	global_store_dwordx2 v[50:51], v[34:35], off offset:64
	v_lshlrev_b32_e32 v34, 16, v144
	v_mul_f32_e32 v38, v2, v38
	v_mul_f32_e32 v34, v38, v34
	v_mul_f32_e32 v38, v45, v52
	v_and_b32_e32 v35, 0xffff0000, v144
	v_mul_f32_e32 v38, v3, v38
	v_mul_f32_e32 v35, v38, v35
	v_mul_f32_e32 v38, v42, v52
	v_lshlrev_b32_e32 v36, 16, v145
	v_mul_f32_e32 v38, v4, v38
	v_mul_f32_e32 v36, v38, v36
	v_mul_f32_e32 v38, v43, v52
	v_and_b32_e32 v37, 0xffff0000, v145
	v_mul_f32_e32 v38, v5, v38
	v_mul_f32_e32 v37, v38, v37
	v_cvt_pk_bf16_f32 v34, v34, v35
	v_cvt_pk_bf16_f32 v35, v36, v37
	global_store_dwordx2 v[50:51], v[34:35], off offset:96
	v_mov_b32_e32 v34, v24
	v_mov_b32_e32 v35, v20
	v_mov_b32_e32 v36, v25
	v_mov_b32_e32 v37, v21
	v_pk_add_f32 v[34:35], v[34:35], v[36:37]
	v_mov_b32_e32 v36, v22
	v_mov_b32_e32 v37, v18
	v_pk_add_f32 v[34:35], v[36:37], v[34:35]
	v_mov_b32_e32 v36, v23
	v_mov_b32_e32 v37, v19
	v_pk_add_f32 v[34:35], v[36:37], v[34:35]
	v_mov_b32_e32 v36, v33
	v_add_f32_e32 v34, 0, v34
	v_add_f32_e32 v38, v34, v35
	v_mov_b32_e32 v34, v32
	v_mov_b32_e32 v35, v28
	v_mov_b32_e32 v37, v29
	v_pk_add_f32 v[34:35], v[34:35], v[36:37]
	v_mov_b32_e32 v36, v30
	v_mov_b32_e32 v37, v26
	v_pk_add_f32 v[34:35], v[36:37], v[34:35]
	v_mov_b32_e32 v36, v31
	v_mov_b32_e32 v37, v27
	v_pk_add_f32 v[34:35], v[36:37], v[34:35]
	v_lshlrev_b32_e32 v39, 16, v143
	v_add_f32_e32 v34, v38, v34
	v_add_f32_e32 v34, v34, v35
	ds_bpermute_b32 v35, v54, v34
	v_and_b32_e32 v40, 0xffff0000, v143
	s_waitcnt lgkmcnt(0)
	v_add_f32_e32 v34, v34, v35
	ds_bpermute_b32 v35, v55, v34
	s_waitcnt lgkmcnt(0)
	v_add_f32_e32 v35, v34, v35
	v_fmac_f32_e32 v25, 0xbc800000, v35
	v_fmamk_f32 v24, v35, 0xbc800000, v24
	v_mul_f32_e32 v38, v25, v25
	v_fmac_f32_e32 v38, v24, v24
	v_fmamk_f32 v22, v35, 0xbc800000, v22
	v_fmac_f32_e32 v38, v22, v22
	v_fmac_f32_e32 v23, 0xbc800000, v35
	v_fmac_f32_e32 v38, v23, v23
	v_fmamk_f32 v20, v35, 0xbc800000, v20
	v_fmac_f32_e32 v38, v20, v20
	v_fmac_f32_e32 v21, 0xbc800000, v35
	v_mul_f32_e32 v34, 0x3c800000, v35
	v_fmac_f32_e32 v38, v21, v21
	v_fmamk_f32 v18, v35, 0xbc800000, v18
	v_fmac_f32_e32 v38, v18, v18
	v_fmac_f32_e32 v19, 0xbc800000, v35
	v_pk_add_f32 v[32:33], v[32:33], v[34:35] op_sel_hi:[1,0] neg_lo:[0,1] neg_hi:[0,1]
	v_fmac_f32_e32 v38, v19, v19
	v_pk_mul_f32 v[36:37], v[32:33], v[32:33]
	s_nop 0
	v_add_f32_e32 v35, v36, v38
	v_add_f32_e32 v35, v37, v35
	v_pk_add_f32 v[30:31], v[30:31], v[34:35] op_sel_hi:[1,0] neg_lo:[0,1] neg_hi:[0,1]
	v_and_b32_e32 v38, 0xffff0000, v142
	v_pk_mul_f32 v[36:37], v[30:31], v[30:31]
	s_nop 0
	v_add_f32_e32 v35, v36, v35
	v_add_f32_e32 v35, v37, v35
	v_pk_add_f32 v[28:29], v[28:29], v[34:35] op_sel_hi:[1,0] neg_lo:[0,1] neg_hi:[0,1]
	s_nop 0
	v_pk_mul_f32 v[36:37], v[28:29], v[28:29]
	s_nop 0
	v_add_f32_e32 v35, v36, v35
	v_pk_add_f32 v[26:27], v[26:27], v[34:35] op_sel_hi:[1,0] neg_lo:[0,1] neg_hi:[0,1]
	v_add_f32_e32 v36, v37, v35
	v_pk_mul_f32 v[34:35], v[26:27], v[26:27]
	v_lshlrev_b32_e32 v37, 16, v142
	v_add_f32_e32 v34, v34, v36
	v_add_f32_e32 v34, v35, v34
	ds_bpermute_b32 v35, v54, v34
	s_waitcnt lgkmcnt(0)
	v_add_f32_e32 v34, v34, v35
	ds_bpermute_b32 v35, v55, v34
	s_waitcnt lgkmcnt(0)
	v_add_f32_e32 v34, v34, v35
	v_fmamk_f32 v34, v34, 0x3c800000, v203
	v_cmp_gt_f32_e32 vcc, s28, v34
	v_mul_f32_e32 v35, 0x4b800000, v34
	s_nop 0
	v_cndmask_b32_e32 v34, v34, v35, vcc
	v_rsq_f32_e32 v34, v34
	s_nop 0
	v_mul_f32_e32 v35, 0x45800000, v34
	v_cndmask_b32_e32 v36, v34, v35, vcc
	v_cmp_gt_i32_e32 vcc, s37, v166
	v_mul_f32_e32 v24, v24, v36
	v_mul_f32_e32 v22, v22, v36
	v_cndmask_b32_e64 v34, 3, 1, vcc
	v_add_u32_e32 v34, v34, v166
	v_ashrrev_i32_e32 v35, 31, v34
	v_lshlrev_b64 v[34:35], 11, v[34:35]
	v_mul_f32_e32 v14, v14, v24
	v_mul_f32_e32 v24, v25, v36
	v_mul_f32_e32 v16, v16, v22
	v_mul_f32_e32 v22, v23, v36
	v_lshl_add_u64 v[34:35], s[8:9], 0, v[34:35]
	v_mul_f32_e32 v15, v15, v24
	v_mul_f32_e32 v17, v17, v22
	v_lshl_add_u64 v[34:35], v[34:35], 0, v[134:135]
	v_mul_f32_e32 v14, v14, v37
	v_mul_f32_e32 v15, v15, v38
	v_mul_f32_e32 v16, v16, v39
	v_mul_f32_e32 v17, v17, v40
	v_cvt_pk_bf16_f32 v14, v14, v15
	v_cvt_pk_bf16_f32 v15, v16, v17
	v_lshl_add_u64 v[16:17], v[34:35], 0, v[0:1]
	v_lshl_add_u64 v[22:23], v[16:17], 0, s[54:55]
	v_add_co_u32_e32 v16, vcc, s34, v16
	v_lshlrev_b32_e32 v0, 16, v140
	s_nop 0
	v_addc_co_u32_e32 v17, vcc, 0, v17, vcc
	global_store_dwordx2 v[16:17], v[14:15], off offset:1280
	v_mul_f32_e32 v17, v20, v36
	v_mul_f32_e32 v10, v10, v17
	v_mul_f32_e32 v0, v10, v0
	v_mul_f32_e32 v10, v21, v36
	v_mul_f32_e32 v10, v11, v10
	v_mul_f32_e32 v11, v18, v36
	v_and_b32_e32 v14, 0xffff0000, v140
	v_mul_f32_e32 v11, v12, v11
	v_mul_f32_e32 v12, v19, v36
	v_mul_f32_e32 v10, v10, v14
	v_mul_f32_e32 v12, v13, v12
	v_mul_f32_e32 v13, v32, v36
	v_cvt_pk_bf16_f32 v10, v0, v10
	v_lshlrev_b32_e32 v0, 16, v138
	v_mul_f32_e32 v6, v6, v13
	v_lshlrev_b32_e32 v15, 16, v141
	v_mul_f32_e32 v0, v6, v0
	v_mul_f32_e32 v6, v33, v36
	v_and_b32_e32 v16, 0xffff0000, v141
	v_mul_f32_e32 v11, v11, v15
	v_mul_f32_e32 v6, v7, v6
	v_mul_f32_e32 v7, v30, v36
	v_mul_f32_e32 v12, v12, v16
	v_cvt_pk_bf16_f32 v11, v11, v12
	global_store_dwordx2 v[22:23], v[10:11], off offset:32
	v_and_b32_e32 v10, 0xffff0000, v138
	v_mul_f32_e32 v7, v8, v7
	v_mul_f32_e32 v8, v31, v36
	v_mul_f32_e32 v6, v6, v10
	v_mul_f32_e32 v8, v9, v8
	v_mul_f32_e32 v9, v28, v36
	v_lshlrev_b32_e32 v11, 16, v139
	v_cvt_pk_bf16_f32 v6, v0, v6
	v_lshlrev_b32_e32 v0, 16, v136
	v_mul_f32_e32 v2, v2, v9
	v_and_b32_e32 v12, 0xffff0000, v139
	v_mul_f32_e32 v7, v7, v11
	v_mul_f32_e32 v0, v2, v0
	v_mul_f32_e32 v2, v29, v36
	v_mul_f32_e32 v8, v8, v12
	v_cvt_pk_bf16_f32 v7, v7, v8
	v_mul_f32_e32 v2, v3, v2
	v_mul_f32_e32 v3, v26, v36
	global_store_dwordx2 v[22:23], v[6:7], off offset:64
	v_and_b32_e32 v6, 0xffff0000, v136
	v_lshlrev_b32_e32 v7, 16, v137
	v_mul_f32_e32 v3, v4, v3
	v_mul_f32_e32 v4, v27, v36
	v_cmp_le_i32_e32 vcc, s2, v164
	v_and_b32_e32 v8, 0xffff0000, v137
	v_mul_f32_e32 v2, v2, v6
	v_mul_f32_e32 v3, v3, v7
	v_mul_f32_e32 v4, v5, v4
	s_or_b64 s[40:41], vcc, s[40:41]
	v_mul_f32_e32 v4, v4, v8
	v_cvt_pk_bf16_f32 v2, v0, v2
	v_cvt_pk_bf16_f32 v3, v3, v4
	global_store_dwordx2 v[22:23], v[2:3], off offset:96
	s_andn2_b64 exec, exec, s[40:41]
	s_cbranch_execnz .LBB0_149

.LBB0_345:
	v_ashrrev_i32_e32 v0, 6, v156
	v_readlane_b32 s0, v252, 4
	s_waitcnt vmcnt(0) lgkmcnt(0)
	s_barrier
	s_lshr_b32 s0, s0, 3
	s_lshr_b32 s1, s33, 3
	v_mul_lo_u32 v4, v0, s1
	v_add_u32_e32 v4, s0, v4
	s_movk_i32 s0, 0x618
	v_cmp_gt_i32_e32 vcc, s0, v4
	s_and_saveexec_b64 s[0:1], vcc
	v_readlane_b32 s46, v255, 5
	v_readlane_b32 s12, v252, 32
	v_readlane_b32 s47, v255, 6
	v_readlane_b32 s48, v255, 7
	v_readlane_b32 s13, v252, 33
	v_readlane_b32 s49, v255, 10
	s_mov_b32 s16, 0x2aaaaaab
	s_mov_b32 s17, 0x186000
	s_mov_b32 s18, 0x104000
	s_mov_b32 s19, 0x82000
	s_mov_b64 s[22:23], 0x82000
	s_mov_b64 s[34:35], 0x104000
	s_mov_b64 s[38:39], 0x186000
	s_cbranch_execz .LBB0_348
	v_readlane_b32 s2, v252, 2
	v_and_b32_e32 v6, 1, v4
	v_cmp_eq_u32_e32 vcc, 0, v6
	v_add_u32_e32 v0, s2, v162
	v_lshlrev_b32_e32 v5, 3, v0
	v_mov_b32_e32 v0, 0x14604000
	v_mov_b32_e32 v2, 0x139d4000
	v_cndmask_b32_e32 v0, v0, v2, vcc
	v_lshl_add_u64 v[2:3], s[8:9], 0, v[0:1]
	s_mov_b64 s[14:15], 0
	v_readlane_b32 s3, v252, 3
